# up and down sample-row skinny GEMMs hand-pipelined; U sample rows stored fragment-linear so the down skinny reads 1KB contiguous per load; nt on W loads
# speedup vs baseline: 1.0119x; 1.0087x over previous
; #define LAS __attribute__((address_space(3)))
; #define SK_LOAD(buf, c) do { _Pragma("unroll") for (int nt = 0; nt < 2; ++nt) fb[buf][nt] = *(const bf16x8*)(pb + nt * rs + 32 * (c)); \
;         _Pragma("unroll") for (int mt = 0; mt < NMT; ++mt) fa[buf][mt] = *(const bf16x8*)(pa + mt * rs + 32 * (c)); } while (0)
; #define SK_MMA(buf) do { _Pragma("unroll") for (int mt = 0; mt < NMT; ++mt) _Pragma("unroll") for (int nt = 0; nt < 2; ++nt) \
;         acc[mt][nt] = __builtin_amdgcn_mfma_f32_16x16x32_bf16(fa[buf][mt], fb[buf][nt], acc[mt][nt], 0, 0, 0); } while (0)
; template <int MT, class Epi>
; DI void skinny_unit(LAS unsigned char* lds, const bf16_t* A, const bf16_t* Wt, int K, int cgi, int k0, int row0, const Epi& E, int tid) {
;     const int lane = tid & 63, wid = tid >> 6, fr = lane & 15, fq = lane >> 4;
;     const int c0 = cgi * 32;
;     constexpr int NMT = 2 * MT;
;     const bf16_t* pa = A + (size_t)(row0 + fr) * K + k0 + wid * 256 + 8 * fq;
;     const bf16_t* pb = Wt + (size_t)(c0 + fr) * K + k0 + wid * 256 + 8 * fq;
;     const size_t rs = (size_t)16 * K;
;     f32x4 acc[NMT][2];
; #pragma unroll
;     for (int i = 0; i < NMT; ++i) { acc[i][0] = (f32x4){0.f, 0.f, 0.f, 0.f}; acc[i][1] = (f32x4){0.f, 0.f, 0.f, 0.f}; }
;     bf16x8 fb[3][2], fa[3][NMT];
;     ...
;     SK_LOAD(0, 0); SK_LOAD(1, 1);
;     SK_LOAD(2, 2); SK_MMA(0);
;     SK_LOAD(0, 3); SK_MMA(1);
;     SK_LOAD(1, 4); SK_MMA(2);
;     SK_LOAD(2, 5); SK_MMA(0);
; __global__ void __launch_bounds__(512, 2) fwd_kernel(Args a) {
;     ...
;         for (int u = bx; u < FF / 32; u += G) skinny_unit<4>(lds, XG + (size_t)LP * DM, WUP, DM, u, 0, 0, SE, tid);
.LBB0_636:
	s_cmpk_gt_i32 s92, 0xff
	s_cbranch_scc1 .LBB0_639
	s_waitcnt lgkmcnt(0)
	s_mov_b64 exec, -1
	v_and_b32_e32 v70, 15, v253
	v_bfe_u32 v71, v253, 4, 2
	v_lshrrev_b32_e32 v72, 6, v253
	v_mul_u32_u24_e32 v64, 0x1000, v70
	v_lshl_add_u32 v64, v72, 9, v64
	v_lshl_add_u32 v64, v71, 4, v64
	v_mul_u32_u24_e32 v65, 0x4000, v72
	v_lshl_add_u32 v65, v71, 9, v65
	v_lshl_add_u32 v65, v70, 2, v65
	v_lshrrev_b32_e32 v73, 2, v253
	v_and_b32_e32 v74, 3, v253
	v_lshlrev_b32_e32 v66, 7, v73
	v_lshl_add_u32 v66, v74, 5, v66
	v_add_u32_e32 v67, 0x10000, v66
	v_and_b32_e32 v68, 15, v73
	v_lshl_add_u32 v68, v74, 4, v68
	v_lshlrev_b32_e32 v68, 4, v68
	v_lshl_add_u32 v68, v72, 10, v68
	s_add_u32 s2, s60, 0x7f00000
	s_addc_u32 s3, s61, 0
	s_add_u32 s6, s60, 0x1f00000
	s_addc_u32 s7, s61, 0
	s_mov_b32 s0, s92
.Lsk6_loop:
	s_add_u32 s14, s2, 0x0
	s_addc_u32 s15, s3, 0
	s_add_u32 s24, s2, 0x10000
	s_addc_u32 s25, s3, 0
	s_add_u32 s26, s2, 0x20000
	s_addc_u32 s27, s3, 0
	s_add_u32 s28, s2, 0x30000
	s_addc_u32 s29, s3, 0
	s_add_u32 s30, s2, 0x40000
	s_addc_u32 s31, s3, 0
	s_add_u32 s34, s2, 0x50000
	s_addc_u32 s35, s3, 0
	s_add_u32 s36, s2, 0x60000
	s_addc_u32 s37, s3, 0
	s_add_u32 s38, s2, 0x70000
	s_addc_u32 s39, s3, 0
	s_lshl_b32 s8, s0, 17
	s_add_u32 s8, s6, s8
	s_addc_u32 s9, s7, 0
	s_add_u32 s10, s8, 0x10000
	s_addc_u32 s11, s9, 0
	s_lshl_b32 s12, s0, 13
	s_add_u32 s12, s12, 0x12400000
	s_add_u32 s12, s60, s12
	s_addc_u32 s13, s61, 0
	global_load_dwordx4 v[108:111], v64, s[8:9] offset:0 nt
	global_load_dwordx4 v[148:151], v64, s[8:9] offset:64 nt
	global_load_dwordx4 v[112:115], v64, s[10:11] offset:0 nt
	global_load_dwordx4 v[152:155], v64, s[10:11] offset:64 nt
	global_load_dwordx4 v[76:79], v64, s[14:15] offset:0
	global_load_dwordx4 v[116:119], v64, s[14:15] offset:64
	global_load_dwordx4 v[80:83], v64, s[24:25] offset:0
	global_load_dwordx4 v[120:123], v64, s[24:25] offset:64
	global_load_dwordx4 v[84:87], v64, s[26:27] offset:0
	global_load_dwordx4 v[124:127], v64, s[26:27] offset:64
	global_load_dwordx4 v[88:91], v64, s[28:29] offset:0
	global_load_dwordx4 v[128:131], v64, s[28:29] offset:64
	global_load_dwordx4 v[92:95], v64, s[30:31] offset:0
	global_load_dwordx4 v[132:135], v64, s[30:31] offset:64
	global_load_dwordx4 v[96:99], v64, s[34:35] offset:0
	global_load_dwordx4 v[136:139], v64, s[34:35] offset:64
	global_load_dwordx4 v[100:103], v64, s[36:37] offset:0
	global_load_dwordx4 v[140:143], v64, s[36:37] offset:64
	global_load_dwordx4 v[104:107], v64, s[38:39] offset:0
	global_load_dwordx4 v[144:147], v64, s[38:39] offset:64
	global_load_dwordx4 v[188:191], v64, s[8:9] offset:128 nt
	global_load_dwordx4 v[228:231], v64, s[8:9] offset:192 nt
	global_load_dwordx4 v[192:195], v64, s[10:11] offset:128 nt
	global_load_dwordx4 v[232:235], v64, s[10:11] offset:192 nt
	global_load_dwordx4 v[156:159], v64, s[14:15] offset:128
	global_load_dwordx4 v[196:199], v64, s[14:15] offset:192
	global_load_dwordx4 v[160:163], v64, s[24:25] offset:128
	global_load_dwordx4 v[200:203], v64, s[24:25] offset:192
	global_load_dwordx4 v[164:167], v64, s[26:27] offset:128
	global_load_dwordx4 v[204:207], v64, s[26:27] offset:192
	global_load_dwordx4 v[168:171], v64, s[28:29] offset:128
	global_load_dwordx4 v[208:211], v64, s[28:29] offset:192
	global_load_dwordx4 v[172:175], v64, s[30:31] offset:128
	global_load_dwordx4 v[212:215], v64, s[30:31] offset:192
	global_load_dwordx4 v[176:179], v64, s[34:35] offset:128
	global_load_dwordx4 v[216:219], v64, s[34:35] offset:192
	global_load_dwordx4 v[180:183], v64, s[36:37] offset:128
	global_load_dwordx4 v[220:223], v64, s[36:37] offset:192
	global_load_dwordx4 v[184:187], v64, s[38:39] offset:128
	global_load_dwordx4 v[224:227], v64, s[38:39] offset:192
	s_waitcnt vmcnt(20)
	v_mfma_f32_16x16x32_bf16 v[0:3], v[76:79], v[108:111], 0
	v_mfma_f32_16x16x32_bf16 v[4:7], v[76:79], v[112:115], 0
	v_mfma_f32_16x16x32_bf16 v[8:11], v[80:83], v[108:111], 0
	v_mfma_f32_16x16x32_bf16 v[12:15], v[80:83], v[112:115], 0
	v_mfma_f32_16x16x32_bf16 v[16:19], v[84:87], v[108:111], 0
	v_mfma_f32_16x16x32_bf16 v[20:23], v[84:87], v[112:115], 0
	v_mfma_f32_16x16x32_bf16 v[24:27], v[88:91], v[108:111], 0
	v_mfma_f32_16x16x32_bf16 v[28:31], v[88:91], v[112:115], 0
	v_mfma_f32_16x16x32_bf16 v[32:35], v[92:95], v[108:111], 0
	v_mfma_f32_16x16x32_bf16 v[36:39], v[92:95], v[112:115], 0
	v_mfma_f32_16x16x32_bf16 v[40:43], v[96:99], v[108:111], 0
	v_mfma_f32_16x16x32_bf16 v[44:47], v[96:99], v[112:115], 0
	v_mfma_f32_16x16x32_bf16 v[48:51], v[100:103], v[108:111], 0
	v_mfma_f32_16x16x32_bf16 v[52:55], v[100:103], v[112:115], 0
	v_mfma_f32_16x16x32_bf16 v[56:59], v[104:107], v[108:111], 0
	v_mfma_f32_16x16x32_bf16 v[60:63], v[104:107], v[112:115], 0
	v_mfma_f32_16x16x32_bf16 v[0:3], v[116:119], v[148:151], v[0:3]
	v_mfma_f32_16x16x32_bf16 v[4:7], v[116:119], v[152:155], v[4:7]
	v_mfma_f32_16x16x32_bf16 v[8:11], v[120:123], v[148:151], v[8:11]
	v_mfma_f32_16x16x32_bf16 v[12:15], v[120:123], v[152:155], v[12:15]
	v_mfma_f32_16x16x32_bf16 v[16:19], v[124:127], v[148:151], v[16:19]
	v_mfma_f32_16x16x32_bf16 v[20:23], v[124:127], v[152:155], v[20:23]
	v_mfma_f32_16x16x32_bf16 v[24:27], v[128:131], v[148:151], v[24:27]
	v_mfma_f32_16x16x32_bf16 v[28:31], v[128:131], v[152:155], v[28:31]
	v_mfma_f32_16x16x32_bf16 v[32:35], v[132:135], v[148:151], v[32:35]
	v_mfma_f32_16x16x32_bf16 v[36:39], v[132:135], v[152:155], v[36:39]
	v_mfma_f32_16x16x32_bf16 v[40:43], v[136:139], v[148:151], v[40:43]
	v_mfma_f32_16x16x32_bf16 v[44:47], v[136:139], v[152:155], v[44:47]
	v_mfma_f32_16x16x32_bf16 v[48:51], v[140:143], v[148:151], v[48:51]
	v_mfma_f32_16x16x32_bf16 v[52:55], v[140:143], v[152:155], v[52:55]
	v_mfma_f32_16x16x32_bf16 v[56:59], v[144:147], v[148:151], v[56:59]
	v_mfma_f32_16x16x32_bf16 v[60:63], v[144:147], v[152:155], v[60:63]
	global_load_dwordx4 v[108:111], v64, s[8:9] offset:256 nt
	global_load_dwordx4 v[148:151], v64, s[8:9] offset:320 nt
	global_load_dwordx4 v[112:115], v64, s[10:11] offset:256 nt
	global_load_dwordx4 v[152:155], v64, s[10:11] offset:320 nt
	global_load_dwordx4 v[76:79], v64, s[14:15] offset:256
	global_load_dwordx4 v[116:119], v64, s[14:15] offset:320
	global_load_dwordx4 v[80:83], v64, s[24:25] offset:256
	global_load_dwordx4 v[120:123], v64, s[24:25] offset:320
	global_load_dwordx4 v[84:87], v64, s[26:27] offset:256
	global_load_dwordx4 v[124:127], v64, s[26:27] offset:320
	global_load_dwordx4 v[88:91], v64, s[28:29] offset:256
	global_load_dwordx4 v[128:131], v64, s[28:29] offset:320
	global_load_dwordx4 v[92:95], v64, s[30:31] offset:256
	global_load_dwordx4 v[132:135], v64, s[30:31] offset:320
	global_load_dwordx4 v[96:99], v64, s[34:35] offset:256
	global_load_dwordx4 v[136:139], v64, s[34:35] offset:320
	global_load_dwordx4 v[100:103], v64, s[36:37] offset:256
	global_load_dwordx4 v[140:143], v64, s[36:37] offset:320
	global_load_dwordx4 v[104:107], v64, s[38:39] offset:256
	global_load_dwordx4 v[144:147], v64, s[38:39] offset:320
	s_waitcnt vmcnt(20)
; #define SK_LOAD(buf, c) do { _Pragma("unroll") for (int nt = 0; nt < 2; ++nt) fb[buf][nt] = *(const bf16x8*)(pb + nt * rs + 32 * (c)); \
;         _Pragma("unroll") for (int mt = 0; mt < NMT; ++mt) fa[buf][mt] = *(const bf16x8*)(pa + mt * rs + 32 * (c)); } while (0)
; #define SK_MMA(buf) do { _Pragma("unroll") for (int mt = 0; mt < NMT; ++mt) _Pragma("unroll") for (int nt = 0; nt < 2; ++nt) \
;         acc[mt][nt] = __builtin_amdgcn_mfma_f32_16x16x32_bf16(fa[buf][mt], fb[buf][nt], acc[mt][nt], 0, 0, 0); } while (0)
; template <int MT, class Epi>
; DI void skinny_unit(LAS unsigned char* lds, const bf16_t* A, const bf16_t* Wt, int K, int cgi, int k0, int row0, const Epi& E, int tid) {
;     ...
;     SK_LOAD(0, 0); SK_LOAD(1, 1);
;     SK_LOAD(2, 2); SK_MMA(0);
;     SK_LOAD(0, 3); SK_MMA(1);
;     SK_LOAD(1, 4); SK_MMA(2);
;     SK_LOAD(2, 5); SK_MMA(0);
;     SK_LOAD(0, 6); SK_MMA(1);
;     SK_LOAD(1, 7); SK_MMA(2);
;     SK_MMA(0); SK_MMA(1);
	v_mfma_f32_16x16x32_bf16 v[0:3], v[156:159], v[188:191], v[0:3]
	v_mfma_f32_16x16x32_bf16 v[4:7], v[156:159], v[192:195], v[4:7]
	v_mfma_f32_16x16x32_bf16 v[8:11], v[160:163], v[188:191], v[8:11]
	v_mfma_f32_16x16x32_bf16 v[12:15], v[160:163], v[192:195], v[12:15]
	v_mfma_f32_16x16x32_bf16 v[16:19], v[164:167], v[188:191], v[16:19]
	v_mfma_f32_16x16x32_bf16 v[20:23], v[164:167], v[192:195], v[20:23]
	v_mfma_f32_16x16x32_bf16 v[24:27], v[168:171], v[188:191], v[24:27]
	v_mfma_f32_16x16x32_bf16 v[28:31], v[168:171], v[192:195], v[28:31]
	v_mfma_f32_16x16x32_bf16 v[32:35], v[172:175], v[188:191], v[32:35]
	v_mfma_f32_16x16x32_bf16 v[36:39], v[172:175], v[192:195], v[36:39]
	v_mfma_f32_16x16x32_bf16 v[40:43], v[176:179], v[188:191], v[40:43]
	v_mfma_f32_16x16x32_bf16 v[44:47], v[176:179], v[192:195], v[44:47]
	v_mfma_f32_16x16x32_bf16 v[48:51], v[180:183], v[188:191], v[48:51]
	v_mfma_f32_16x16x32_bf16 v[52:55], v[180:183], v[192:195], v[52:55]
	v_mfma_f32_16x16x32_bf16 v[56:59], v[184:187], v[188:191], v[56:59]
	v_mfma_f32_16x16x32_bf16 v[60:63], v[184:187], v[192:195], v[60:63]
	v_mfma_f32_16x16x32_bf16 v[0:3], v[196:199], v[228:231], v[0:3]
	v_mfma_f32_16x16x32_bf16 v[4:7], v[196:199], v[232:235], v[4:7]
	v_mfma_f32_16x16x32_bf16 v[8:11], v[200:203], v[228:231], v[8:11]
	v_mfma_f32_16x16x32_bf16 v[12:15], v[200:203], v[232:235], v[12:15]
	v_mfma_f32_16x16x32_bf16 v[16:19], v[204:207], v[228:231], v[16:19]
	v_mfma_f32_16x16x32_bf16 v[20:23], v[204:207], v[232:235], v[20:23]
	v_mfma_f32_16x16x32_bf16 v[24:27], v[208:211], v[228:231], v[24:27]
	v_mfma_f32_16x16x32_bf16 v[28:31], v[208:211], v[232:235], v[28:31]
	v_mfma_f32_16x16x32_bf16 v[32:35], v[212:215], v[228:231], v[32:35]
	v_mfma_f32_16x16x32_bf16 v[36:39], v[212:215], v[232:235], v[36:39]
	v_mfma_f32_16x16x32_bf16 v[40:43], v[216:219], v[228:231], v[40:43]
	v_mfma_f32_16x16x32_bf16 v[44:47], v[216:219], v[232:235], v[44:47]
	v_mfma_f32_16x16x32_bf16 v[48:51], v[220:223], v[228:231], v[48:51]
	v_mfma_f32_16x16x32_bf16 v[52:55], v[220:223], v[232:235], v[52:55]
	v_mfma_f32_16x16x32_bf16 v[56:59], v[224:227], v[228:231], v[56:59]
	v_mfma_f32_16x16x32_bf16 v[60:63], v[224:227], v[232:235], v[60:63]
	global_load_dwordx4 v[188:191], v64, s[8:9] offset:384 nt
	global_load_dwordx4 v[228:231], v64, s[8:9] offset:448 nt
	global_load_dwordx4 v[192:195], v64, s[10:11] offset:384 nt
	global_load_dwordx4 v[232:235], v64, s[10:11] offset:448 nt
	global_load_dwordx4 v[156:159], v64, s[14:15] offset:384
	global_load_dwordx4 v[196:199], v64, s[14:15] offset:448
	global_load_dwordx4 v[160:163], v64, s[24:25] offset:384
	global_load_dwordx4 v[200:203], v64, s[24:25] offset:448
	global_load_dwordx4 v[164:167], v64, s[26:27] offset:384
	global_load_dwordx4 v[204:207], v64, s[26:27] offset:448
	global_load_dwordx4 v[168:171], v64, s[28:29] offset:384
	global_load_dwordx4 v[208:211], v64, s[28:29] offset:448
	global_load_dwordx4 v[172:175], v64, s[30:31] offset:384
	global_load_dwordx4 v[212:215], v64, s[30:31] offset:448
	global_load_dwordx4 v[176:179], v64, s[34:35] offset:384
	global_load_dwordx4 v[216:219], v64, s[34:35] offset:448
	global_load_dwordx4 v[180:183], v64, s[36:37] offset:384
	global_load_dwordx4 v[220:223], v64, s[36:37] offset:448
	global_load_dwordx4 v[184:187], v64, s[38:39] offset:384
	global_load_dwordx4 v[224:227], v64, s[38:39] offset:448
	s_waitcnt vmcnt(20)
	v_mfma_f32_16x16x32_bf16 v[0:3], v[76:79], v[108:111], v[0:3]
	v_mfma_f32_16x16x32_bf16 v[4:7], v[76:79], v[112:115], v[4:7]
	v_mfma_f32_16x16x32_bf16 v[8:11], v[80:83], v[108:111], v[8:11]
	v_mfma_f32_16x16x32_bf16 v[12:15], v[80:83], v[112:115], v[12:15]
	v_mfma_f32_16x16x32_bf16 v[16:19], v[84:87], v[108:111], v[16:19]
	v_mfma_f32_16x16x32_bf16 v[20:23], v[84:87], v[112:115], v[20:23]
	v_mfma_f32_16x16x32_bf16 v[24:27], v[88:91], v[108:111], v[24:27]
	v_mfma_f32_16x16x32_bf16 v[28:31], v[88:91], v[112:115], v[28:31]
	v_mfma_f32_16x16x32_bf16 v[32:35], v[92:95], v[108:111], v[32:35]
	v_mfma_f32_16x16x32_bf16 v[36:39], v[92:95], v[112:115], v[36:39]
	v_mfma_f32_16x16x32_bf16 v[40:43], v[96:99], v[108:111], v[40:43]
	v_mfma_f32_16x16x32_bf16 v[44:47], v[96:99], v[112:115], v[44:47]
	v_mfma_f32_16x16x32_bf16 v[48:51], v[100:103], v[108:111], v[48:51]
	v_mfma_f32_16x16x32_bf16 v[52:55], v[100:103], v[112:115], v[52:55]
	v_mfma_f32_16x16x32_bf16 v[56:59], v[104:107], v[108:111], v[56:59]
	v_mfma_f32_16x16x32_bf16 v[60:63], v[104:107], v[112:115], v[60:63]
	v_mfma_f32_16x16x32_bf16 v[0:3], v[116:119], v[148:151], v[0:3]
	v_mfma_f32_16x16x32_bf16 v[4:7], v[116:119], v[152:155], v[4:7]
	v_mfma_f32_16x16x32_bf16 v[8:11], v[120:123], v[148:151], v[8:11]
	v_mfma_f32_16x16x32_bf16 v[12:15], v[120:123], v[152:155], v[12:15]
	v_mfma_f32_16x16x32_bf16 v[16:19], v[124:127], v[148:151], v[16:19]
	v_mfma_f32_16x16x32_bf16 v[20:23], v[124:127], v[152:155], v[20:23]
	v_mfma_f32_16x16x32_bf16 v[24:27], v[128:131], v[148:151], v[24:27]
	v_mfma_f32_16x16x32_bf16 v[28:31], v[128:131], v[152:155], v[28:31]
	v_mfma_f32_16x16x32_bf16 v[32:35], v[132:135], v[148:151], v[32:35]
	v_mfma_f32_16x16x32_bf16 v[36:39], v[132:135], v[152:155], v[36:39]
	v_mfma_f32_16x16x32_bf16 v[40:43], v[136:139], v[148:151], v[40:43]
	v_mfma_f32_16x16x32_bf16 v[44:47], v[136:139], v[152:155], v[44:47]
	v_mfma_f32_16x16x32_bf16 v[48:51], v[140:143], v[148:151], v[48:51]
	v_mfma_f32_16x16x32_bf16 v[52:55], v[140:143], v[152:155], v[52:55]
	v_mfma_f32_16x16x32_bf16 v[56:59], v[144:147], v[148:151], v[56:59]
	v_mfma_f32_16x16x32_bf16 v[60:63], v[144:147], v[152:155], v[60:63]
	s_waitcnt vmcnt(0)
; #define LAS __attribute__((address_space(3)))
; template <int MT, class Epi>
; DI void skinny_unit(LAS unsigned char* lds, const bf16_t* A, const bf16_t* Wt, int K, int cgi, int k0, int row0, const Epi& E, int tid) {
;     ...
;     constexpr int NR = 32 * MT;
;     LAS float* red = (LAS float*)lds;
; #pragma unroll
;     for (int mt = 0; mt < NMT; ++mt)
; #pragma unroll
;         for (int nt = 0; nt < 2; ++nt)
; #pragma unroll
;             for (int j = 0; j < 4; ++j) red[(wid * NR + mt * 16 + 4 * fq + j) * 32 + nt * 16 + fr] = acc[mt][nt][j];
;     __syncthreads();
;     if (MT == 4) {
;         const int row = tid >> 2, c8 = (tid & 3) * 8;
;         f32x4 sa = {0.f, 0.f, 0.f, 0.f}, sb = {0.f, 0.f, 0.f, 0.f};
; #pragma unroll
;         for (int w = 0; w < 8; ++w) { sa += *(const LAS f32x4*)(red + (w * NR + row) * 32 + c8); sb += *(const LAS f32x4*)(red + (w * NR + row) * 32 + c8 + 4); }
;         E(row0 + row, c0 + c8, sa); E(row0 + row, c0 + c8 + 4, sb);
;     } else if (tid < 8 * NR) {
;         const int row = tid >> 3, c4 = (tid & 7) * 4;
;         f32x4 sa = {0.f, 0.f, 0.f, 0.f};
; #pragma unroll
;         for (int w = 0; w < 8; ++w) sa += *(const LAS f32x4*)(red + (w * NR + row) * 32 + c4);
;         E(row0 + row, c0 + c4, sa);
;     }
;     __syncthreads();
; }
	v_mfma_f32_16x16x32_bf16 v[0:3], v[156:159], v[188:191], v[0:3]
	v_mfma_f32_16x16x32_bf16 v[4:7], v[156:159], v[192:195], v[4:7]
	v_mfma_f32_16x16x32_bf16 v[8:11], v[160:163], v[188:191], v[8:11]
	v_mfma_f32_16x16x32_bf16 v[12:15], v[160:163], v[192:195], v[12:15]
	v_mfma_f32_16x16x32_bf16 v[16:19], v[164:167], v[188:191], v[16:19]
	v_mfma_f32_16x16x32_bf16 v[20:23], v[164:167], v[192:195], v[20:23]
	v_mfma_f32_16x16x32_bf16 v[24:27], v[168:171], v[188:191], v[24:27]
	v_mfma_f32_16x16x32_bf16 v[28:31], v[168:171], v[192:195], v[28:31]
	v_mfma_f32_16x16x32_bf16 v[32:35], v[172:175], v[188:191], v[32:35]
	v_mfma_f32_16x16x32_bf16 v[36:39], v[172:175], v[192:195], v[36:39]
	v_mfma_f32_16x16x32_bf16 v[40:43], v[176:179], v[188:191], v[40:43]
	v_mfma_f32_16x16x32_bf16 v[44:47], v[176:179], v[192:195], v[44:47]
	v_mfma_f32_16x16x32_bf16 v[48:51], v[180:183], v[188:191], v[48:51]
	v_mfma_f32_16x16x32_bf16 v[52:55], v[180:183], v[192:195], v[52:55]
	v_mfma_f32_16x16x32_bf16 v[56:59], v[184:187], v[188:191], v[56:59]
	v_mfma_f32_16x16x32_bf16 v[60:63], v[184:187], v[192:195], v[60:63]
	v_mfma_f32_16x16x32_bf16 v[0:3], v[196:199], v[228:231], v[0:3]
	v_mfma_f32_16x16x32_bf16 v[4:7], v[196:199], v[232:235], v[4:7]
	v_mfma_f32_16x16x32_bf16 v[8:11], v[200:203], v[228:231], v[8:11]
	v_mfma_f32_16x16x32_bf16 v[12:15], v[200:203], v[232:235], v[12:15]
	v_mfma_f32_16x16x32_bf16 v[16:19], v[204:207], v[228:231], v[16:19]
	v_mfma_f32_16x16x32_bf16 v[20:23], v[204:207], v[232:235], v[20:23]
	v_mfma_f32_16x16x32_bf16 v[24:27], v[208:211], v[228:231], v[24:27]
	v_mfma_f32_16x16x32_bf16 v[28:31], v[208:211], v[232:235], v[28:31]
	v_mfma_f32_16x16x32_bf16 v[32:35], v[212:215], v[228:231], v[32:35]
	v_mfma_f32_16x16x32_bf16 v[36:39], v[212:215], v[232:235], v[36:39]
	v_mfma_f32_16x16x32_bf16 v[40:43], v[216:219], v[228:231], v[40:43]
	v_mfma_f32_16x16x32_bf16 v[44:47], v[216:219], v[232:235], v[44:47]
	v_mfma_f32_16x16x32_bf16 v[48:51], v[220:223], v[228:231], v[48:51]
	v_mfma_f32_16x16x32_bf16 v[52:55], v[220:223], v[232:235], v[52:55]
	v_mfma_f32_16x16x32_bf16 v[56:59], v[224:227], v[228:231], v[56:59]
	v_mfma_f32_16x16x32_bf16 v[60:63], v[224:227], v[232:235], v[60:63]
	v_add_u32_e32 v77, 0x800, v65
	v_add_u32_e32 v78, 0x1000, v65
	v_add_u32_e32 v79, 0x1800, v65
	v_add_u32_e32 v80, 0x2000, v65
	v_add_u32_e32 v81, 0x2800, v65
	v_add_u32_e32 v82, 0x3000, v65
	v_add_u32_e32 v83, 0x3800, v65
	s_nop 7
	s_nop 3
	ds_write2_b32 v65, v0, v4 offset1:16
	ds_write2_b32 v65, v1, v5 offset0:32 offset1:48
	ds_write2_b32 v65, v2, v6 offset0:64 offset1:80
	ds_write2_b32 v65, v3, v7 offset0:96 offset1:112
	ds_write2_b32 v77, v8, v12 offset1:16
	ds_write2_b32 v77, v9, v13 offset0:32 offset1:48
	ds_write2_b32 v77, v10, v14 offset0:64 offset1:80
	ds_write2_b32 v77, v11, v15 offset0:96 offset1:112
	ds_write2_b32 v78, v16, v20 offset1:16
	ds_write2_b32 v78, v17, v21 offset0:32 offset1:48
	ds_write2_b32 v78, v18, v22 offset0:64 offset1:80
	ds_write2_b32 v78, v19, v23 offset0:96 offset1:112
	ds_write2_b32 v79, v24, v28 offset1:16
	ds_write2_b32 v79, v25, v29 offset0:32 offset1:48
	ds_write2_b32 v79, v26, v30 offset0:64 offset1:80
	ds_write2_b32 v79, v27, v31 offset0:96 offset1:112
	ds_write2_b32 v80, v32, v36 offset1:16
	ds_write2_b32 v80, v33, v37 offset0:32 offset1:48
	ds_write2_b32 v80, v34, v38 offset0:64 offset1:80
	ds_write2_b32 v80, v35, v39 offset0:96 offset1:112
	ds_write2_b32 v81, v40, v44 offset1:16
	ds_write2_b32 v81, v41, v45 offset0:32 offset1:48
	ds_write2_b32 v81, v42, v46 offset0:64 offset1:80
	ds_write2_b32 v81, v43, v47 offset0:96 offset1:112
	ds_write2_b32 v82, v48, v52 offset1:16
	ds_write2_b32 v82, v49, v53 offset0:32 offset1:48
	ds_write2_b32 v82, v50, v54 offset0:64 offset1:80
	ds_write2_b32 v82, v51, v55 offset0:96 offset1:112
	ds_write2_b32 v83, v56, v60 offset1:16
	ds_write2_b32 v83, v57, v61 offset0:32 offset1:48
	ds_write2_b32 v83, v58, v62 offset0:64 offset1:80
	ds_write2_b32 v83, v59, v63 offset0:96 offset1:112
	s_waitcnt lgkmcnt(0)
	s_barrier
	ds_read_b128 v[76:79], v66 offset:0
	ds_read_b128 v[80:83], v66 offset:16
	ds_read_b128 v[84:87], v66 offset:16384
	ds_read_b128 v[88:91], v66 offset:16400
	ds_read_b128 v[92:95], v66 offset:32768
	ds_read_b128 v[96:99], v66 offset:32784
	ds_read_b128 v[100:103], v66 offset:49152
	ds_read_b128 v[104:107], v66 offset:49168
	ds_read_b128 v[108:111], v67 offset:0
	ds_read_b128 v[112:115], v67 offset:16
	ds_read_b128 v[116:119], v67 offset:16384
	ds_read_b128 v[120:123], v67 offset:16400
	ds_read_b128 v[124:127], v67 offset:32768
	ds_read_b128 v[128:131], v67 offset:32784
	ds_read_b128 v[132:135], v67 offset:49152
	ds_read_b128 v[136:139], v67 offset:49168
	s_waitcnt lgkmcnt(12)
	v_pk_add_f32 v[76:77], v[76:77], v[84:85]
	v_pk_add_f32 v[78:79], v[78:79], v[86:87]
	v_pk_add_f32 v[80:81], v[80:81], v[88:89]
	v_pk_add_f32 v[82:83], v[82:83], v[90:91]
	s_waitcnt lgkmcnt(10)
	v_pk_add_f32 v[76:77], v[76:77], v[92:93]
	v_pk_add_f32 v[78:79], v[78:79], v[94:95]
	v_pk_add_f32 v[80:81], v[80:81], v[96:97]
	v_pk_add_f32 v[82:83], v[82:83], v[98:99]
	s_waitcnt lgkmcnt(8)
	v_pk_add_f32 v[76:77], v[76:77], v[100:101]
	v_pk_add_f32 v[78:79], v[78:79], v[102:103]
	v_pk_add_f32 v[80:81], v[80:81], v[104:105]
	v_pk_add_f32 v[82:83], v[82:83], v[106:107]
	s_waitcnt lgkmcnt(6)
	v_pk_add_f32 v[76:77], v[76:77], v[108:109]
	v_pk_add_f32 v[78:79], v[78:79], v[110:111]
	v_pk_add_f32 v[80:81], v[80:81], v[112:113]
	v_pk_add_f32 v[82:83], v[82:83], v[114:115]
	s_waitcnt lgkmcnt(4)
	v_pk_add_f32 v[76:77], v[76:77], v[116:117]
	v_pk_add_f32 v[78:79], v[78:79], v[118:119]
	v_pk_add_f32 v[80:81], v[80:81], v[120:121]
	v_pk_add_f32 v[82:83], v[82:83], v[122:123]
	s_waitcnt lgkmcnt(2)
	v_pk_add_f32 v[76:77], v[76:77], v[124:125]
	v_pk_add_f32 v[78:79], v[78:79], v[126:127]
	v_pk_add_f32 v[80:81], v[80:81], v[128:129]
	v_pk_add_f32 v[82:83], v[82:83], v[130:131]
	s_waitcnt lgkmcnt(0)
	v_pk_add_f32 v[76:77], v[76:77], v[132:133]
	v_pk_add_f32 v[78:79], v[78:79], v[134:135]
	v_pk_add_f32 v[80:81], v[80:81], v[136:137]
	v_pk_add_f32 v[82:83], v[82:83], v[138:139]
	v_max_f32_e32 v76, 0, v76
	v_max_f32_e32 v77, 0, v77
	v_max_f32_e32 v78, 0, v78
	v_max_f32_e32 v79, 0, v79
	v_max_f32_e32 v80, 0, v80
	v_max_f32_e32 v81, 0, v81
	v_max_f32_e32 v82, 0, v82
	v_max_f32_e32 v83, 0, v83
	v_pk_mul_f32 v[76:77], v[76:77], v[76:77]
	v_pk_mul_f32 v[78:79], v[78:79], v[78:79]
	v_pk_mul_f32 v[80:81], v[80:81], v[80:81]
	v_pk_mul_f32 v[82:83], v[82:83], v[82:83]
	v_cvt_pk_bf16_f32 v84, v76, v77
	v_cvt_pk_bf16_f32 v85, v78, v79
	v_cvt_pk_bf16_f32 v86, v80, v81
	v_cvt_pk_bf16_f32 v87, v82, v83
	global_store_dwordx4 v68, v[84:87], s[12:13]
	s_add_i32 s0, s0, s64
	s_cmpk_lt_i32 s0, 0x100
	s_barrier
	s_cbranch_scc1 .Lsk6_loop

; #define LAS __attribute__((address_space(3)))
; #define SK_LOAD(buf, c) do { _Pragma("unroll") for (int nt = 0; nt < 2; ++nt) fb[buf][nt] = *(const bf16x8*)(pb + nt * rs + 32 * (c)); \
;         _Pragma("unroll") for (int mt = 0; mt < NMT; ++mt) fa[buf][mt] = *(const bf16x8*)(pa + mt * rs + 32 * (c)); } while (0)
; #define SK_MMA(buf) do { _Pragma("unroll") for (int mt = 0; mt < NMT; ++mt) _Pragma("unroll") for (int nt = 0; nt < 2; ++nt) \
;         acc[mt][nt] = __builtin_amdgcn_mfma_f32_16x16x32_bf16(fa[buf][mt], fb[buf][nt], acc[mt][nt], 0, 0, 0); } while (0)
; template <int MT, class Epi>
; DI void skinny_unit(LAS unsigned char* lds, const bf16_t* A, const bf16_t* Wt, int K, int cgi, int k0, int row0, const Epi& E, int tid) {
;     const int lane = tid & 63, wid = tid >> 6, fr = lane & 15, fq = lane >> 4;
;     const int c0 = cgi * 32;
;     constexpr int NMT = 2 * MT;
;     const bf16_t* pa = A + (size_t)(row0 + fr) * K + k0 + wid * 256 + 8 * fq;
;     const bf16_t* pb = Wt + (size_t)(c0 + fr) * K + k0 + wid * 256 + 8 * fq;
;     const size_t rs = (size_t)16 * K;
;     f32x4 acc[NMT][2];
; #pragma unroll
;     for (int i = 0; i < NMT; ++i) { acc[i][0] = (f32x4){0.f, 0.f, 0.f, 0.f}; acc[i][1] = (f32x4){0.f, 0.f, 0.f, 0.f}; }
;     bf16x8 fb[3][2], fa[3][NMT];
;     ...
;     SK_LOAD(0, 0); SK_LOAD(1, 1);
;     SK_LOAD(2, 2); SK_MMA(0);
;     SK_LOAD(0, 3); SK_MMA(1);
;     SK_LOAD(1, 4); SK_MMA(2);
;     SK_LOAD(2, 5); SK_MMA(0);
; __global__ void __launch_bounds__(512, 2) fwd_kernel(Args a) {
;     ...
;         if (bx & 1) for (int u = bx; u < 4 * (DM / 32); u += G) { const SkSlab SE{SLAB + (size_t)(u & 3) * NS * DM}; skinny_unit<4>(lds, U + (size_t)LP * FF, WDN, FF, u >> 2, (u & 3) * 2048, 0, SE, tid); }
.LBB0_693:
	s_cmp_lt_i32 s62, 8
	s_cselect_b64 s[2:3], -1, 0
	s_add_u32 s4, s60, 0xa300000
	s_addc_u32 s5, s61, 0
	s_and_b64 s[6:7], s[2:3], s[0:1]
	s_andn2_b64 vcc, exec, s[6:7]
	s_cbranch_vccnz .LBB0_727
	s_and_b32 s0, s92, 1
	s_cmp_eq_u32 s0, 0
	s_cselect_b64 s[8:9], -1, 0
	s_cmp_eq_u32 s0, 1
	s_cselect_b64 s[2:3], -1, 0
	s_cmpk_lt_i32 s92, 0x100
	s_cselect_b64 s[10:11], -1, 0
	s_and_b64 s[2:3], s[10:11], s[2:3]
	v_bfe_u32 v141, v253, 4, 2
	s_mov_b32 s1, 0
	s_and_b64 vcc, exec, s[2:3]
	v_and_b32_e32 v28, 15, v253
	v_lshlrev_b32_e32 v128, 3, v141
	v_lshlrev_b32_e32 v130, 4, v141
	v_lshrrev_b32_e32 v29, 2, v253
	v_lshlrev_b32_e32 v154, 3, v253
	s_cbranch_vccz .LBB0_698
	s_waitcnt lgkmcnt(0)
	s_mov_b64 exec, -1
	v_and_b32_e32 v70, 15, v253
	v_bfe_u32 v71, v253, 4, 2
	v_lshrrev_b32_e32 v72, 6, v253
	v_mul_u32_u24_e32 v64, 0x4000, v70
	v_lshl_add_u32 v64, v72, 9, v64
	v_lshl_add_u32 v64, v71, 4, v64
	v_readfirstlane_b32 s1, v72
	v_and_b32_e32 v69, 63, v253
	v_lshlrev_b32_e32 v69, 4, v69
	v_mul_u32_u24_e32 v65, 0x4000, v72
	v_lshl_add_u32 v65, v71, 9, v65
	v_lshl_add_u32 v65, v70, 2, v65
	v_lshrrev_b32_e32 v73, 2, v253
	v_and_b32_e32 v74, 3, v253
	v_lshlrev_b32_e32 v66, 7, v73
	v_lshl_add_u32 v66, v74, 5, v66
	v_add_u32_e32 v67, 0x10000, v66
	v_lshlrev_b32_e32 v68, 13, v73
	v_lshl_add_u32 v68, v74, 5, v68
	s_add_u32 s2, s60, 0x12400000
	s_addc_u32 s3, s61, 0
	s_add_u32 s10, s60, 0x3f00000
	s_addc_u32 s11, s61, 0
	s_lshl_b32 s1, s1, 16
	s_add_u32 s2, s2, s1
	s_addc_u32 s3, s3, 0
	s_mov_b32 s0, s92
.Lsk7a_loop:
	s_and_b32 s17, s0, 3
	s_lshl_b32 s16, s17, 12
	s_lshl_b32 s24, s17, 19
	s_add_u32 s24, s2, s24
	s_addc_u32 s25, s3, 0
	s_lshr_b32 s14, s0, 2
	s_lshl_b32 s12, s14, 19
	s_add_u32 s12, s12, s16
	s_add_u32 s12, s10, s12
	s_addc_u32 s13, s11, 0
	s_lshl_b32 s16, s17, 20
	s_lshl_b32 s14, s14, 7
	s_add_u32 s16, s16, s14
	s_add_u32 s16, s16, 0x13c00000
	s_add_u32 s16, s60, s16
	s_addc_u32 s17, s61, 0
	s_add_u32 s14, s12, 0x40000
	s_addc_u32 s15, s13, 0
	global_load_dwordx4 v[108:111], v64, s[12:13] offset:0 nt
	global_load_dwordx4 v[148:151], v64, s[12:13] offset:64 nt
	global_load_dwordx4 v[112:115], v64, s[14:15] offset:0 nt
	global_load_dwordx4 v[152:155], v64, s[14:15] offset:64 nt
	global_load_dwordx4 v[76:79], v69, s[24:25] offset:0
	global_load_dwordx4 v[80:83], v69, s[24:25] offset:1024
	global_load_dwordx4 v[84:87], v69, s[24:25] offset:2048
	global_load_dwordx4 v[88:91], v69, s[24:25] offset:3072
	s_add_u32 s24, s24, 0x1000
	s_addc_u32 s25, s25, 0
	global_load_dwordx4 v[92:95], v69, s[24:25] offset:0
	global_load_dwordx4 v[96:99], v69, s[24:25] offset:1024
	global_load_dwordx4 v[100:103], v69, s[24:25] offset:2048
	global_load_dwordx4 v[104:107], v69, s[24:25] offset:3072
	s_add_u32 s24, s24, 0x1000
	s_addc_u32 s25, s25, 0
	global_load_dwordx4 v[116:119], v69, s[24:25] offset:0
	global_load_dwordx4 v[120:123], v69, s[24:25] offset:1024
	global_load_dwordx4 v[124:127], v69, s[24:25] offset:2048
	global_load_dwordx4 v[128:131], v69, s[24:25] offset:3072
	s_add_u32 s24, s24, 0x1000
	s_addc_u32 s25, s25, 0
	global_load_dwordx4 v[132:135], v69, s[24:25] offset:0
	global_load_dwordx4 v[136:139], v69, s[24:25] offset:1024
	global_load_dwordx4 v[140:143], v69, s[24:25] offset:2048
	global_load_dwordx4 v[144:147], v69, s[24:25] offset:3072
	s_add_u32 s24, s24, 0x1000
	s_addc_u32 s25, s25, 0
	global_load_dwordx4 v[188:191], v64, s[12:13] offset:128 nt
	global_load_dwordx4 v[228:231], v64, s[12:13] offset:192 nt
	global_load_dwordx4 v[192:195], v64, s[14:15] offset:128 nt
	global_load_dwordx4 v[232:235], v64, s[14:15] offset:192 nt
	global_load_dwordx4 v[156:159], v69, s[24:25] offset:0
	global_load_dwordx4 v[160:163], v69, s[24:25] offset:1024
	global_load_dwordx4 v[164:167], v69, s[24:25] offset:2048
	global_load_dwordx4 v[168:171], v69, s[24:25] offset:3072
	s_add_u32 s24, s24, 0x1000
	s_addc_u32 s25, s25, 0
	global_load_dwordx4 v[172:175], v69, s[24:25] offset:0
	global_load_dwordx4 v[176:179], v69, s[24:25] offset:1024
	global_load_dwordx4 v[180:183], v69, s[24:25] offset:2048
	global_load_dwordx4 v[184:187], v69, s[24:25] offset:3072
	s_add_u32 s24, s24, 0x1000
	s_addc_u32 s25, s25, 0
	global_load_dwordx4 v[196:199], v69, s[24:25] offset:0
	global_load_dwordx4 v[200:203], v69, s[24:25] offset:1024
	global_load_dwordx4 v[204:207], v69, s[24:25] offset:2048
	global_load_dwordx4 v[208:211], v69, s[24:25] offset:3072
	s_add_u32 s24, s24, 0x1000
	s_addc_u32 s25, s25, 0
	global_load_dwordx4 v[212:215], v69, s[24:25] offset:0
	global_load_dwordx4 v[216:219], v69, s[24:25] offset:1024
	global_load_dwordx4 v[220:223], v69, s[24:25] offset:2048
	global_load_dwordx4 v[224:227], v69, s[24:25] offset:3072
	s_add_u32 s24, s24, 0x1000
	s_addc_u32 s25, s25, 0
	s_waitcnt vmcnt(20)
; #define SK_LOAD(buf, c) do { _Pragma("unroll") for (int nt = 0; nt < 2; ++nt) fb[buf][nt] = *(const bf16x8*)(pb + nt * rs + 32 * (c)); \
;         _Pragma("unroll") for (int mt = 0; mt < NMT; ++mt) fa[buf][mt] = *(const bf16x8*)(pa + mt * rs + 32 * (c)); } while (0)
; #define SK_MMA(buf) do { _Pragma("unroll") for (int mt = 0; mt < NMT; ++mt) _Pragma("unroll") for (int nt = 0; nt < 2; ++nt) \
;         acc[mt][nt] = __builtin_amdgcn_mfma_f32_16x16x32_bf16(fa[buf][mt], fb[buf][nt], acc[mt][nt], 0, 0, 0); } while (0)
; template <int MT, class Epi>
; DI void skinny_unit(LAS unsigned char* lds, const bf16_t* A, const bf16_t* Wt, int K, int cgi, int k0, int row0, const Epi& E, int tid) {
;     ...
;     SK_LOAD(0, 0); SK_LOAD(1, 1);
;     SK_LOAD(2, 2); SK_MMA(0);
;     SK_LOAD(0, 3); SK_MMA(1);
;     SK_LOAD(1, 4); SK_MMA(2);
;     SK_LOAD(2, 5); SK_MMA(0);
;     SK_LOAD(0, 6); SK_MMA(1);
;     SK_LOAD(1, 7); SK_MMA(2);
;     SK_MMA(0); SK_MMA(1);
	v_mfma_f32_16x16x32_bf16 v[0:3], v[76:79], v[108:111], 0
	v_mfma_f32_16x16x32_bf16 v[4:7], v[76:79], v[112:115], 0
	v_mfma_f32_16x16x32_bf16 v[8:11], v[80:83], v[108:111], 0
	v_mfma_f32_16x16x32_bf16 v[12:15], v[80:83], v[112:115], 0
	v_mfma_f32_16x16x32_bf16 v[16:19], v[84:87], v[108:111], 0
	v_mfma_f32_16x16x32_bf16 v[20:23], v[84:87], v[112:115], 0
	v_mfma_f32_16x16x32_bf16 v[24:27], v[88:91], v[108:111], 0
	v_mfma_f32_16x16x32_bf16 v[28:31], v[88:91], v[112:115], 0
	v_mfma_f32_16x16x32_bf16 v[32:35], v[92:95], v[108:111], 0
	v_mfma_f32_16x16x32_bf16 v[36:39], v[92:95], v[112:115], 0
	v_mfma_f32_16x16x32_bf16 v[40:43], v[96:99], v[108:111], 0
	v_mfma_f32_16x16x32_bf16 v[44:47], v[96:99], v[112:115], 0
	v_mfma_f32_16x16x32_bf16 v[48:51], v[100:103], v[108:111], 0
	v_mfma_f32_16x16x32_bf16 v[52:55], v[100:103], v[112:115], 0
	v_mfma_f32_16x16x32_bf16 v[56:59], v[104:107], v[108:111], 0
	v_mfma_f32_16x16x32_bf16 v[60:63], v[104:107], v[112:115], 0
	v_mfma_f32_16x16x32_bf16 v[0:3], v[116:119], v[148:151], v[0:3]
	v_mfma_f32_16x16x32_bf16 v[4:7], v[116:119], v[152:155], v[4:7]
	v_mfma_f32_16x16x32_bf16 v[8:11], v[120:123], v[148:151], v[8:11]
	v_mfma_f32_16x16x32_bf16 v[12:15], v[120:123], v[152:155], v[12:15]
	v_mfma_f32_16x16x32_bf16 v[16:19], v[124:127], v[148:151], v[16:19]
	v_mfma_f32_16x16x32_bf16 v[20:23], v[124:127], v[152:155], v[20:23]
	v_mfma_f32_16x16x32_bf16 v[24:27], v[128:131], v[148:151], v[24:27]
	v_mfma_f32_16x16x32_bf16 v[28:31], v[128:131], v[152:155], v[28:31]
	v_mfma_f32_16x16x32_bf16 v[32:35], v[132:135], v[148:151], v[32:35]
	v_mfma_f32_16x16x32_bf16 v[36:39], v[132:135], v[152:155], v[36:39]
	v_mfma_f32_16x16x32_bf16 v[40:43], v[136:139], v[148:151], v[40:43]
	v_mfma_f32_16x16x32_bf16 v[44:47], v[136:139], v[152:155], v[44:47]
	v_mfma_f32_16x16x32_bf16 v[48:51], v[140:143], v[148:151], v[48:51]
	v_mfma_f32_16x16x32_bf16 v[52:55], v[140:143], v[152:155], v[52:55]
	v_mfma_f32_16x16x32_bf16 v[56:59], v[144:147], v[148:151], v[56:59]
	v_mfma_f32_16x16x32_bf16 v[60:63], v[144:147], v[152:155], v[60:63]
	global_load_dwordx4 v[108:111], v64, s[12:13] offset:256 nt
	global_load_dwordx4 v[148:151], v64, s[12:13] offset:320 nt
	global_load_dwordx4 v[112:115], v64, s[14:15] offset:256 nt
	global_load_dwordx4 v[152:155], v64, s[14:15] offset:320 nt
	global_load_dwordx4 v[76:79], v69, s[24:25] offset:0
	global_load_dwordx4 v[80:83], v69, s[24:25] offset:1024
	global_load_dwordx4 v[84:87], v69, s[24:25] offset:2048
	global_load_dwordx4 v[88:91], v69, s[24:25] offset:3072
	s_add_u32 s24, s24, 0x1000
	s_addc_u32 s25, s25, 0
	global_load_dwordx4 v[92:95], v69, s[24:25] offset:0
	global_load_dwordx4 v[96:99], v69, s[24:25] offset:1024
	global_load_dwordx4 v[100:103], v69, s[24:25] offset:2048
	global_load_dwordx4 v[104:107], v69, s[24:25] offset:3072
	s_add_u32 s24, s24, 0x1000
	s_addc_u32 s25, s25, 0
	global_load_dwordx4 v[116:119], v69, s[24:25] offset:0
	global_load_dwordx4 v[120:123], v69, s[24:25] offset:1024
	global_load_dwordx4 v[124:127], v69, s[24:25] offset:2048
	global_load_dwordx4 v[128:131], v69, s[24:25] offset:3072
	s_add_u32 s24, s24, 0x1000
	s_addc_u32 s25, s25, 0
	global_load_dwordx4 v[132:135], v69, s[24:25] offset:0
	global_load_dwordx4 v[136:139], v69, s[24:25] offset:1024
	global_load_dwordx4 v[140:143], v69, s[24:25] offset:2048
	global_load_dwordx4 v[144:147], v69, s[24:25] offset:3072
	s_add_u32 s24, s24, 0x1000
	s_addc_u32 s25, s25, 0
	s_waitcnt vmcnt(20)
	v_mfma_f32_16x16x32_bf16 v[0:3], v[156:159], v[188:191], v[0:3]
	v_mfma_f32_16x16x32_bf16 v[4:7], v[156:159], v[192:195], v[4:7]
	v_mfma_f32_16x16x32_bf16 v[8:11], v[160:163], v[188:191], v[8:11]
	v_mfma_f32_16x16x32_bf16 v[12:15], v[160:163], v[192:195], v[12:15]
	v_mfma_f32_16x16x32_bf16 v[16:19], v[164:167], v[188:191], v[16:19]
	v_mfma_f32_16x16x32_bf16 v[20:23], v[164:167], v[192:195], v[20:23]
	v_mfma_f32_16x16x32_bf16 v[24:27], v[168:171], v[188:191], v[24:27]
	v_mfma_f32_16x16x32_bf16 v[28:31], v[168:171], v[192:195], v[28:31]
	v_mfma_f32_16x16x32_bf16 v[32:35], v[172:175], v[188:191], v[32:35]
	v_mfma_f32_16x16x32_bf16 v[36:39], v[172:175], v[192:195], v[36:39]
	v_mfma_f32_16x16x32_bf16 v[40:43], v[176:179], v[188:191], v[40:43]
	v_mfma_f32_16x16x32_bf16 v[44:47], v[176:179], v[192:195], v[44:47]
	v_mfma_f32_16x16x32_bf16 v[48:51], v[180:183], v[188:191], v[48:51]
	v_mfma_f32_16x16x32_bf16 v[52:55], v[180:183], v[192:195], v[52:55]
	v_mfma_f32_16x16x32_bf16 v[56:59], v[184:187], v[188:191], v[56:59]
	v_mfma_f32_16x16x32_bf16 v[60:63], v[184:187], v[192:195], v[60:63]
	v_mfma_f32_16x16x32_bf16 v[0:3], v[196:199], v[228:231], v[0:3]
	v_mfma_f32_16x16x32_bf16 v[4:7], v[196:199], v[232:235], v[4:7]
	v_mfma_f32_16x16x32_bf16 v[8:11], v[200:203], v[228:231], v[8:11]
	v_mfma_f32_16x16x32_bf16 v[12:15], v[200:203], v[232:235], v[12:15]
	v_mfma_f32_16x16x32_bf16 v[16:19], v[204:207], v[228:231], v[16:19]
	v_mfma_f32_16x16x32_bf16 v[20:23], v[204:207], v[232:235], v[20:23]
	v_mfma_f32_16x16x32_bf16 v[24:27], v[208:211], v[228:231], v[24:27]
	v_mfma_f32_16x16x32_bf16 v[28:31], v[208:211], v[232:235], v[28:31]
	v_mfma_f32_16x16x32_bf16 v[32:35], v[212:215], v[228:231], v[32:35]
	v_mfma_f32_16x16x32_bf16 v[36:39], v[212:215], v[232:235], v[36:39]
	v_mfma_f32_16x16x32_bf16 v[40:43], v[216:219], v[228:231], v[40:43]
	v_mfma_f32_16x16x32_bf16 v[44:47], v[216:219], v[232:235], v[44:47]
	v_mfma_f32_16x16x32_bf16 v[48:51], v[220:223], v[228:231], v[48:51]
	v_mfma_f32_16x16x32_bf16 v[52:55], v[220:223], v[232:235], v[52:55]
	v_mfma_f32_16x16x32_bf16 v[56:59], v[224:227], v[228:231], v[56:59]
	v_mfma_f32_16x16x32_bf16 v[60:63], v[224:227], v[232:235], v[60:63]
	global_load_dwordx4 v[188:191], v64, s[12:13] offset:384 nt
	global_load_dwordx4 v[228:231], v64, s[12:13] offset:448 nt
	global_load_dwordx4 v[192:195], v64, s[14:15] offset:384 nt
	global_load_dwordx4 v[232:235], v64, s[14:15] offset:448 nt
	global_load_dwordx4 v[156:159], v69, s[24:25] offset:0
	global_load_dwordx4 v[160:163], v69, s[24:25] offset:1024
	global_load_dwordx4 v[164:167], v69, s[24:25] offset:2048
	global_load_dwordx4 v[168:171], v69, s[24:25] offset:3072
	s_add_u32 s24, s24, 0x1000
	s_addc_u32 s25, s25, 0
	global_load_dwordx4 v[172:175], v69, s[24:25] offset:0
	global_load_dwordx4 v[176:179], v69, s[24:25] offset:1024
	global_load_dwordx4 v[180:183], v69, s[24:25] offset:2048
	global_load_dwordx4 v[184:187], v69, s[24:25] offset:3072
	s_add_u32 s24, s24, 0x1000
	s_addc_u32 s25, s25, 0
	global_load_dwordx4 v[196:199], v69, s[24:25] offset:0
	global_load_dwordx4 v[200:203], v69, s[24:25] offset:1024
	global_load_dwordx4 v[204:207], v69, s[24:25] offset:2048
	global_load_dwordx4 v[208:211], v69, s[24:25] offset:3072
	s_add_u32 s24, s24, 0x1000
	s_addc_u32 s25, s25, 0
	global_load_dwordx4 v[212:215], v69, s[24:25] offset:0
	global_load_dwordx4 v[216:219], v69, s[24:25] offset:1024
	global_load_dwordx4 v[220:223], v69, s[24:25] offset:2048
	global_load_dwordx4 v[224:227], v69, s[24:25] offset:3072
	s_waitcnt vmcnt(20)
; #define LAS __attribute__((address_space(3)))
; #define SK_LOAD(buf, c) do { _Pragma("unroll") for (int nt = 0; nt < 2; ++nt) fb[buf][nt] = *(const bf16x8*)(pb + nt * rs + 32 * (c)); \
;         _Pragma("unroll") for (int mt = 0; mt < NMT; ++mt) fa[buf][mt] = *(const bf16x8*)(pa + mt * rs + 32 * (c)); } while (0)
; #define SK_MMA(buf) do { _Pragma("unroll") for (int mt = 0; mt < NMT; ++mt) _Pragma("unroll") for (int nt = 0; nt < 2; ++nt) \
;         acc[mt][nt] = __builtin_amdgcn_mfma_f32_16x16x32_bf16(fa[buf][mt], fb[buf][nt], acc[mt][nt], 0, 0, 0); } while (0)
; template <int MT, class Epi>
; DI void skinny_unit(LAS unsigned char* lds, const bf16_t* A, const bf16_t* Wt, int K, int cgi, int k0, int row0, const Epi& E, int tid) {
;     ...
;     SK_LOAD(0, 0); SK_LOAD(1, 1);
;     SK_LOAD(2, 2); SK_MMA(0);
;     SK_LOAD(0, 3); SK_MMA(1);
;     SK_LOAD(1, 4); SK_MMA(2);
;     SK_LOAD(2, 5); SK_MMA(0);
;     SK_LOAD(0, 6); SK_MMA(1);
;     SK_LOAD(1, 7); SK_MMA(2);
;     SK_MMA(0); SK_MMA(1);
;     ...
;     constexpr int NR = 32 * MT;
;     LAS float* red = (LAS float*)lds;
; #pragma unroll
;     for (int mt = 0; mt < NMT; ++mt)
; #pragma unroll
;         for (int nt = 0; nt < 2; ++nt)
; #pragma unroll
;             for (int j = 0; j < 4; ++j) red[(wid * NR + mt * 16 + 4 * fq + j) * 32 + nt * 16 + fr] = acc[mt][nt][j];
	v_mfma_f32_16x16x32_bf16 v[0:3], v[76:79], v[108:111], v[0:3]
	v_mfma_f32_16x16x32_bf16 v[4:7], v[76:79], v[112:115], v[4:7]
	v_mfma_f32_16x16x32_bf16 v[8:11], v[80:83], v[108:111], v[8:11]
	v_mfma_f32_16x16x32_bf16 v[12:15], v[80:83], v[112:115], v[12:15]
	v_mfma_f32_16x16x32_bf16 v[16:19], v[84:87], v[108:111], v[16:19]
	v_mfma_f32_16x16x32_bf16 v[20:23], v[84:87], v[112:115], v[20:23]
	v_mfma_f32_16x16x32_bf16 v[24:27], v[88:91], v[108:111], v[24:27]
	v_mfma_f32_16x16x32_bf16 v[28:31], v[88:91], v[112:115], v[28:31]
	v_mfma_f32_16x16x32_bf16 v[32:35], v[92:95], v[108:111], v[32:35]
	v_mfma_f32_16x16x32_bf16 v[36:39], v[92:95], v[112:115], v[36:39]
	v_mfma_f32_16x16x32_bf16 v[40:43], v[96:99], v[108:111], v[40:43]
	v_mfma_f32_16x16x32_bf16 v[44:47], v[96:99], v[112:115], v[44:47]
	v_mfma_f32_16x16x32_bf16 v[48:51], v[100:103], v[108:111], v[48:51]
	v_mfma_f32_16x16x32_bf16 v[52:55], v[100:103], v[112:115], v[52:55]
	v_mfma_f32_16x16x32_bf16 v[56:59], v[104:107], v[108:111], v[56:59]
	v_mfma_f32_16x16x32_bf16 v[60:63], v[104:107], v[112:115], v[60:63]
	v_mfma_f32_16x16x32_bf16 v[0:3], v[116:119], v[148:151], v[0:3]
	v_mfma_f32_16x16x32_bf16 v[4:7], v[116:119], v[152:155], v[4:7]
	v_mfma_f32_16x16x32_bf16 v[8:11], v[120:123], v[148:151], v[8:11]
	v_mfma_f32_16x16x32_bf16 v[12:15], v[120:123], v[152:155], v[12:15]
	v_mfma_f32_16x16x32_bf16 v[16:19], v[124:127], v[148:151], v[16:19]
	v_mfma_f32_16x16x32_bf16 v[20:23], v[124:127], v[152:155], v[20:23]
	v_mfma_f32_16x16x32_bf16 v[24:27], v[128:131], v[148:151], v[24:27]
	v_mfma_f32_16x16x32_bf16 v[28:31], v[128:131], v[152:155], v[28:31]
	v_mfma_f32_16x16x32_bf16 v[32:35], v[132:135], v[148:151], v[32:35]
	v_mfma_f32_16x16x32_bf16 v[36:39], v[132:135], v[152:155], v[36:39]
	v_mfma_f32_16x16x32_bf16 v[40:43], v[136:139], v[148:151], v[40:43]
	v_mfma_f32_16x16x32_bf16 v[44:47], v[136:139], v[152:155], v[44:47]
	v_mfma_f32_16x16x32_bf16 v[48:51], v[140:143], v[148:151], v[48:51]
	v_mfma_f32_16x16x32_bf16 v[52:55], v[140:143], v[152:155], v[52:55]
	v_mfma_f32_16x16x32_bf16 v[56:59], v[144:147], v[148:151], v[56:59]
	v_mfma_f32_16x16x32_bf16 v[60:63], v[144:147], v[152:155], v[60:63]
	s_waitcnt vmcnt(0)
	v_mfma_f32_16x16x32_bf16 v[0:3], v[156:159], v[188:191], v[0:3]
	v_mfma_f32_16x16x32_bf16 v[4:7], v[156:159], v[192:195], v[4:7]
	v_mfma_f32_16x16x32_bf16 v[8:11], v[160:163], v[188:191], v[8:11]
	v_mfma_f32_16x16x32_bf16 v[12:15], v[160:163], v[192:195], v[12:15]
	v_mfma_f32_16x16x32_bf16 v[16:19], v[164:167], v[188:191], v[16:19]
	v_mfma_f32_16x16x32_bf16 v[20:23], v[164:167], v[192:195], v[20:23]
	v_mfma_f32_16x16x32_bf16 v[24:27], v[168:171], v[188:191], v[24:27]
	v_mfma_f32_16x16x32_bf16 v[28:31], v[168:171], v[192:195], v[28:31]
	v_mfma_f32_16x16x32_bf16 v[32:35], v[172:175], v[188:191], v[32:35]
	v_mfma_f32_16x16x32_bf16 v[36:39], v[172:175], v[192:195], v[36:39]
	v_mfma_f32_16x16x32_bf16 v[40:43], v[176:179], v[188:191], v[40:43]
	v_mfma_f32_16x16x32_bf16 v[44:47], v[176:179], v[192:195], v[44:47]
	v_mfma_f32_16x16x32_bf16 v[48:51], v[180:183], v[188:191], v[48:51]
	v_mfma_f32_16x16x32_bf16 v[52:55], v[180:183], v[192:195], v[52:55]
	v_mfma_f32_16x16x32_bf16 v[56:59], v[184:187], v[188:191], v[56:59]
	v_mfma_f32_16x16x32_bf16 v[60:63], v[184:187], v[192:195], v[60:63]
	v_mfma_f32_16x16x32_bf16 v[0:3], v[196:199], v[228:231], v[0:3]
	v_mfma_f32_16x16x32_bf16 v[4:7], v[196:199], v[232:235], v[4:7]
	v_mfma_f32_16x16x32_bf16 v[8:11], v[200:203], v[228:231], v[8:11]
	v_mfma_f32_16x16x32_bf16 v[12:15], v[200:203], v[232:235], v[12:15]
	v_mfma_f32_16x16x32_bf16 v[16:19], v[204:207], v[228:231], v[16:19]
	v_mfma_f32_16x16x32_bf16 v[20:23], v[204:207], v[232:235], v[20:23]
	v_mfma_f32_16x16x32_bf16 v[24:27], v[208:211], v[228:231], v[24:27]
	v_mfma_f32_16x16x32_bf16 v[28:31], v[208:211], v[232:235], v[28:31]
	v_mfma_f32_16x16x32_bf16 v[32:35], v[212:215], v[228:231], v[32:35]
	v_mfma_f32_16x16x32_bf16 v[36:39], v[212:215], v[232:235], v[36:39]
	v_mfma_f32_16x16x32_bf16 v[40:43], v[216:219], v[228:231], v[40:43]
	v_mfma_f32_16x16x32_bf16 v[44:47], v[216:219], v[232:235], v[44:47]
	v_mfma_f32_16x16x32_bf16 v[48:51], v[220:223], v[228:231], v[48:51]
	v_mfma_f32_16x16x32_bf16 v[52:55], v[220:223], v[232:235], v[52:55]
	v_mfma_f32_16x16x32_bf16 v[56:59], v[224:227], v[228:231], v[56:59]
	v_mfma_f32_16x16x32_bf16 v[60:63], v[224:227], v[232:235], v[60:63]
	v_add_u32_e32 v77, 0x800, v65
	v_add_u32_e32 v78, 0x1000, v65
	v_add_u32_e32 v79, 0x1800, v65
	v_add_u32_e32 v80, 0x2000, v65
	v_add_u32_e32 v81, 0x2800, v65
	v_add_u32_e32 v82, 0x3000, v65
	v_add_u32_e32 v83, 0x3800, v65
	s_nop 7
	s_nop 3
	ds_write2_b32 v65, v0, v4 offset1:16
	ds_write2_b32 v65, v1, v5 offset0:32 offset1:48
	ds_write2_b32 v65, v2, v6 offset0:64 offset1:80
	ds_write2_b32 v65, v3, v7 offset0:96 offset1:112
	ds_write2_b32 v77, v8, v12 offset1:16
	ds_write2_b32 v77, v9, v13 offset0:32 offset1:48
	ds_write2_b32 v77, v10, v14 offset0:64 offset1:80
	ds_write2_b32 v77, v11, v15 offset0:96 offset1:112
	ds_write2_b32 v78, v16, v20 offset1:16
	ds_write2_b32 v78, v17, v21 offset0:32 offset1:48
	ds_write2_b32 v78, v18, v22 offset0:64 offset1:80
	ds_write2_b32 v78, v19, v23 offset0:96 offset1:112
	ds_write2_b32 v79, v24, v28 offset1:16
	ds_write2_b32 v79, v25, v29 offset0:32 offset1:48
	ds_write2_b32 v79, v26, v30 offset0:64 offset1:80
	ds_write2_b32 v79, v27, v31 offset0:96 offset1:112
	ds_write2_b32 v80, v32, v36 offset1:16
	ds_write2_b32 v80, v33, v37 offset0:32 offset1:48
	ds_write2_b32 v80, v34, v38 offset0:64 offset1:80
	ds_write2_b32 v80, v35, v39 offset0:96 offset1:112
	ds_write2_b32 v81, v40, v44 offset1:16
	ds_write2_b32 v81, v41, v45 offset0:32 offset1:48
	ds_write2_b32 v81, v42, v46 offset0:64 offset1:80
	ds_write2_b32 v81, v43, v47 offset0:96 offset1:112
	ds_write2_b32 v82, v48, v52 offset1:16
	ds_write2_b32 v82, v49, v53 offset0:32 offset1:48
	ds_write2_b32 v82, v50, v54 offset0:64 offset1:80
	ds_write2_b32 v82, v51, v55 offset0:96 offset1:112
	ds_write2_b32 v83, v56, v60 offset1:16
	ds_write2_b32 v83, v57, v61 offset0:32 offset1:48
	ds_write2_b32 v83, v58, v62 offset0:64 offset1:80
	ds_write2_b32 v83, v59, v63 offset0:96 offset1:112
	s_waitcnt lgkmcnt(0)
	s_barrier
; #define LAS __attribute__((address_space(3)))
; template <int MT, class Epi>
; DI void skinny_unit(LAS unsigned char* lds, const bf16_t* A, const bf16_t* Wt, int K, int cgi, int k0, int row0, const Epi& E, int tid) {
;     ...
;     __syncthreads();
;     if (MT == 4) {
;         const int row = tid >> 2, c8 = (tid & 3) * 8;
;         f32x4 sa = {0.f, 0.f, 0.f, 0.f}, sb = {0.f, 0.f, 0.f, 0.f};
; #pragma unroll
;         for (int w = 0; w < 8; ++w) { sa += *(const LAS f32x4*)(red + (w * NR + row) * 32 + c8); sb += *(const LAS f32x4*)(red + (w * NR + row) * 32 + c8 + 4); }
;         E(row0 + row, c0 + c8, sa); E(row0 + row, c0 + c8 + 4, sb);
;     } else if (tid < 8 * NR) {
;         const int row = tid >> 3, c4 = (tid & 7) * 4;
;         f32x4 sa = {0.f, 0.f, 0.f, 0.f};
; #pragma unroll
;         for (int w = 0; w < 8; ++w) sa += *(const LAS f32x4*)(red + (w * NR + row) * 32 + c4);
;         E(row0 + row, c0 + c4, sa);
;     }
;     __syncthreads();
; }
	ds_read_b128 v[76:79], v66 offset:0
	ds_read_b128 v[80:83], v66 offset:16
	ds_read_b128 v[84:87], v66 offset:16384
	ds_read_b128 v[88:91], v66 offset:16400
	ds_read_b128 v[92:95], v66 offset:32768
	ds_read_b128 v[96:99], v66 offset:32784
	ds_read_b128 v[100:103], v66 offset:49152
	ds_read_b128 v[104:107], v66 offset:49168
	ds_read_b128 v[108:111], v67 offset:0
	ds_read_b128 v[112:115], v67 offset:16
	ds_read_b128 v[116:119], v67 offset:16384
	ds_read_b128 v[120:123], v67 offset:16400
	ds_read_b128 v[124:127], v67 offset:32768
	ds_read_b128 v[128:131], v67 offset:32784
	ds_read_b128 v[132:135], v67 offset:49152
	ds_read_b128 v[136:139], v67 offset:49168
	s_waitcnt lgkmcnt(12)
	v_pk_add_f32 v[76:77], v[76:77], v[84:85]
	v_pk_add_f32 v[78:79], v[78:79], v[86:87]
	v_pk_add_f32 v[80:81], v[80:81], v[88:89]
	v_pk_add_f32 v[82:83], v[82:83], v[90:91]
	s_waitcnt lgkmcnt(10)
	v_pk_add_f32 v[76:77], v[76:77], v[92:93]
	v_pk_add_f32 v[78:79], v[78:79], v[94:95]
	v_pk_add_f32 v[80:81], v[80:81], v[96:97]
	v_pk_add_f32 v[82:83], v[82:83], v[98:99]
	s_waitcnt lgkmcnt(8)
	v_pk_add_f32 v[76:77], v[76:77], v[100:101]
	v_pk_add_f32 v[78:79], v[78:79], v[102:103]
	v_pk_add_f32 v[80:81], v[80:81], v[104:105]
	v_pk_add_f32 v[82:83], v[82:83], v[106:107]
	s_waitcnt lgkmcnt(6)
	v_pk_add_f32 v[76:77], v[76:77], v[108:109]
	v_pk_add_f32 v[78:79], v[78:79], v[110:111]
	v_pk_add_f32 v[80:81], v[80:81], v[112:113]
	v_pk_add_f32 v[82:83], v[82:83], v[114:115]
	s_waitcnt lgkmcnt(4)
	v_pk_add_f32 v[76:77], v[76:77], v[116:117]
	v_pk_add_f32 v[78:79], v[78:79], v[118:119]
	v_pk_add_f32 v[80:81], v[80:81], v[120:121]
	v_pk_add_f32 v[82:83], v[82:83], v[122:123]
	s_waitcnt lgkmcnt(2)
	v_pk_add_f32 v[76:77], v[76:77], v[124:125]
	v_pk_add_f32 v[78:79], v[78:79], v[126:127]
	v_pk_add_f32 v[80:81], v[80:81], v[128:129]
	v_pk_add_f32 v[82:83], v[82:83], v[130:131]
	s_waitcnt lgkmcnt(0)
	v_pk_add_f32 v[76:77], v[76:77], v[132:133]
	v_pk_add_f32 v[78:79], v[78:79], v[134:135]
	v_pk_add_f32 v[80:81], v[80:81], v[136:137]
	v_pk_add_f32 v[82:83], v[82:83], v[138:139]
	global_store_dwordx4 v68, v[76:79], s[16:17]
	global_store_dwordx4 v68, v[80:83], s[16:17] offset:16
	s_add_i32 s0, s0, s64
	s_cmpk_lt_i32 s0, 0x100
	s_barrier
	s_cbranch_scc1 .Lsk7a_loop
	v_bfe_u32 v141, v253, 4, 2
	v_lshlrev_b32_e32 v154, 3, v253
	v_and_b32_e32 v129, 15, v253
	v_lshrrev_b32_e32 v156, 2, v253
	v_lshlrev_b32_e32 v128, 3, v141
	v_lshlrev_b32_e32 v130, 4, v141
	s_branch .LBB0_700

; #define LAS __attribute__((address_space(3)))
; #define SK_LOAD(buf, c) do { _Pragma("unroll") for (int nt = 0; nt < 2; ++nt) fb[buf][nt] = *(const bf16x8*)(pb + nt * rs + 32 * (c)); \
;         _Pragma("unroll") for (int mt = 0; mt < NMT; ++mt) fa[buf][mt] = *(const bf16x8*)(pa + mt * rs + 32 * (c)); } while (0)
; #define SK_MMA(buf) do { _Pragma("unroll") for (int mt = 0; mt < NMT; ++mt) _Pragma("unroll") for (int nt = 0; nt < 2; ++nt) \
;         acc[mt][nt] = __builtin_amdgcn_mfma_f32_16x16x32_bf16(fa[buf][mt], fb[buf][nt], acc[mt][nt], 0, 0, 0); } while (0)
; template <int MT, class Epi>
; DI void skinny_unit(LAS unsigned char* lds, const bf16_t* A, const bf16_t* Wt, int K, int cgi, int k0, int row0, const Epi& E, int tid) {
;     const int lane = tid & 63, wid = tid >> 6, fr = lane & 15, fq = lane >> 4;
;     const int c0 = cgi * 32;
;     constexpr int NMT = 2 * MT;
;     const bf16_t* pa = A + (size_t)(row0 + fr) * K + k0 + wid * 256 + 8 * fq;
;     const bf16_t* pb = Wt + (size_t)(c0 + fr) * K + k0 + wid * 256 + 8 * fq;
;     const size_t rs = (size_t)16 * K;
;     f32x4 acc[NMT][2];
; #pragma unroll
;     for (int i = 0; i < NMT; ++i) { acc[i][0] = (f32x4){0.f, 0.f, 0.f, 0.f}; acc[i][1] = (f32x4){0.f, 0.f, 0.f, 0.f}; }
;     bf16x8 fb[3][2], fa[3][NMT];
;     ...
;     SK_LOAD(0, 0); SK_LOAD(1, 1);
;     SK_LOAD(2, 2); SK_MMA(0);
;     SK_LOAD(0, 3); SK_MMA(1);
;     SK_LOAD(1, 4); SK_MMA(2);
;     SK_LOAD(2, 5); SK_MMA(0);
; __global__ void __launch_bounds__(512, 2) fwd_kernel(Args a) {
;     ...
;         if (!(bx & 1)) for (int u = bx; u < 4 * (DM / 32); u += G) { const SkSlab SE{SLAB + (size_t)(u & 3) * NS * DM}; skinny_unit<4>(lds, U + (size_t)LP * FF, WDN, FF, u >> 2, (u & 3) * 2048, 0, SE, tid); }
.LBB0_724:
	s_and_b64 s[0:1], s[8:9], s[10:11]
	s_andn2_b64 vcc, exec, s[0:1]
	s_cbranch_vccnz .LBB0_727
	s_waitcnt lgkmcnt(0)
	s_mov_b64 exec, -1
	v_and_b32_e32 v70, 15, v253
	v_bfe_u32 v71, v253, 4, 2
	v_lshrrev_b32_e32 v72, 6, v253
	v_mul_u32_u24_e32 v64, 0x4000, v70
	v_lshl_add_u32 v64, v72, 9, v64
	v_lshl_add_u32 v64, v71, 4, v64
	v_readfirstlane_b32 s1, v72
	v_and_b32_e32 v69, 63, v253
	v_lshlrev_b32_e32 v69, 4, v69
	v_mul_u32_u24_e32 v65, 0x4000, v72
	v_lshl_add_u32 v65, v71, 9, v65
	v_lshl_add_u32 v65, v70, 2, v65
	v_lshrrev_b32_e32 v73, 2, v253
	v_and_b32_e32 v74, 3, v253
	v_lshlrev_b32_e32 v66, 7, v73
	v_lshl_add_u32 v66, v74, 5, v66
	v_add_u32_e32 v67, 0x10000, v66
	v_lshlrev_b32_e32 v68, 13, v73
	v_lshl_add_u32 v68, v74, 5, v68
	s_add_u32 s2, s60, 0x12400000
	s_addc_u32 s3, s61, 0
	s_add_u32 s8, s60, 0x3f00000
	s_addc_u32 s9, s61, 0
	s_lshl_b32 s1, s1, 16
	s_add_u32 s2, s2, s1
	s_addc_u32 s3, s3, 0
	s_mov_b32 s0, s92
.Lsk7b_loop:
	s_and_b32 s15, s0, 3
	s_lshl_b32 s14, s15, 12
	s_lshl_b32 s16, s15, 19
	s_add_u32 s16, s2, s16
	s_addc_u32 s17, s3, 0
	s_lshr_b32 s12, s0, 2
	s_lshl_b32 s10, s12, 19
	s_add_u32 s10, s10, s14
	s_add_u32 s10, s8, s10
	s_addc_u32 s11, s9, 0
	s_lshl_b32 s14, s15, 20
	s_lshl_b32 s12, s12, 7
	s_add_u32 s14, s14, s12
	s_add_u32 s14, s14, 0x13c00000
	s_add_u32 s14, s60, s14
	s_addc_u32 s15, s61, 0
	s_add_u32 s12, s10, 0x40000
	s_addc_u32 s13, s11, 0
	global_load_dwordx4 v[108:111], v64, s[10:11] offset:0 nt
	global_load_dwordx4 v[148:151], v64, s[10:11] offset:64 nt
	global_load_dwordx4 v[112:115], v64, s[12:13] offset:0 nt
	global_load_dwordx4 v[152:155], v64, s[12:13] offset:64 nt
	global_load_dwordx4 v[76:79], v69, s[16:17] offset:0
	global_load_dwordx4 v[80:83], v69, s[16:17] offset:1024
	global_load_dwordx4 v[84:87], v69, s[16:17] offset:2048
	global_load_dwordx4 v[88:91], v69, s[16:17] offset:3072
	s_add_u32 s16, s16, 0x1000
	s_addc_u32 s17, s17, 0
	global_load_dwordx4 v[92:95], v69, s[16:17] offset:0
	global_load_dwordx4 v[96:99], v69, s[16:17] offset:1024
	global_load_dwordx4 v[100:103], v69, s[16:17] offset:2048
	global_load_dwordx4 v[104:107], v69, s[16:17] offset:3072
	s_add_u32 s16, s16, 0x1000
	s_addc_u32 s17, s17, 0
	global_load_dwordx4 v[116:119], v69, s[16:17] offset:0
	global_load_dwordx4 v[120:123], v69, s[16:17] offset:1024
	global_load_dwordx4 v[124:127], v69, s[16:17] offset:2048
	global_load_dwordx4 v[128:131], v69, s[16:17] offset:3072
	s_add_u32 s16, s16, 0x1000
	s_addc_u32 s17, s17, 0
	global_load_dwordx4 v[132:135], v69, s[16:17] offset:0
	global_load_dwordx4 v[136:139], v69, s[16:17] offset:1024
	global_load_dwordx4 v[140:143], v69, s[16:17] offset:2048
	global_load_dwordx4 v[144:147], v69, s[16:17] offset:3072
	s_add_u32 s16, s16, 0x1000
	s_addc_u32 s17, s17, 0
	global_load_dwordx4 v[188:191], v64, s[10:11] offset:128 nt
	global_load_dwordx4 v[228:231], v64, s[10:11] offset:192 nt
	global_load_dwordx4 v[192:195], v64, s[12:13] offset:128 nt
	global_load_dwordx4 v[232:235], v64, s[12:13] offset:192 nt
	global_load_dwordx4 v[156:159], v69, s[16:17] offset:0
	global_load_dwordx4 v[160:163], v69, s[16:17] offset:1024
	global_load_dwordx4 v[164:167], v69, s[16:17] offset:2048
	global_load_dwordx4 v[168:171], v69, s[16:17] offset:3072
	s_add_u32 s16, s16, 0x1000
	s_addc_u32 s17, s17, 0
	global_load_dwordx4 v[172:175], v69, s[16:17] offset:0
	global_load_dwordx4 v[176:179], v69, s[16:17] offset:1024
	global_load_dwordx4 v[180:183], v69, s[16:17] offset:2048
	global_load_dwordx4 v[184:187], v69, s[16:17] offset:3072
	s_add_u32 s16, s16, 0x1000
	s_addc_u32 s17, s17, 0
	global_load_dwordx4 v[196:199], v69, s[16:17] offset:0
	global_load_dwordx4 v[200:203], v69, s[16:17] offset:1024
	global_load_dwordx4 v[204:207], v69, s[16:17] offset:2048
	global_load_dwordx4 v[208:211], v69, s[16:17] offset:3072
	s_add_u32 s16, s16, 0x1000
	s_addc_u32 s17, s17, 0
	global_load_dwordx4 v[212:215], v69, s[16:17] offset:0
	global_load_dwordx4 v[216:219], v69, s[16:17] offset:1024
	global_load_dwordx4 v[220:223], v69, s[16:17] offset:2048
	global_load_dwordx4 v[224:227], v69, s[16:17] offset:3072
	s_add_u32 s16, s16, 0x1000
	s_addc_u32 s17, s17, 0
	s_waitcnt vmcnt(20)
	v_mfma_f32_16x16x32_bf16 v[0:3], v[76:79], v[108:111], 0
	v_mfma_f32_16x16x32_bf16 v[4:7], v[76:79], v[112:115], 0
	v_mfma_f32_16x16x32_bf16 v[8:11], v[80:83], v[108:111], 0
	v_mfma_f32_16x16x32_bf16 v[12:15], v[80:83], v[112:115], 0
	v_mfma_f32_16x16x32_bf16 v[16:19], v[84:87], v[108:111], 0
	v_mfma_f32_16x16x32_bf16 v[20:23], v[84:87], v[112:115], 0
	v_mfma_f32_16x16x32_bf16 v[24:27], v[88:91], v[108:111], 0
	v_mfma_f32_16x16x32_bf16 v[28:31], v[88:91], v[112:115], 0
	v_mfma_f32_16x16x32_bf16 v[32:35], v[92:95], v[108:111], 0
	v_mfma_f32_16x16x32_bf16 v[36:39], v[92:95], v[112:115], 0
	v_mfma_f32_16x16x32_bf16 v[40:43], v[96:99], v[108:111], 0
	v_mfma_f32_16x16x32_bf16 v[44:47], v[96:99], v[112:115], 0
	v_mfma_f32_16x16x32_bf16 v[48:51], v[100:103], v[108:111], 0
	v_mfma_f32_16x16x32_bf16 v[52:55], v[100:103], v[112:115], 0
	v_mfma_f32_16x16x32_bf16 v[56:59], v[104:107], v[108:111], 0
	v_mfma_f32_16x16x32_bf16 v[60:63], v[104:107], v[112:115], 0
	v_mfma_f32_16x16x32_bf16 v[0:3], v[116:119], v[148:151], v[0:3]
	v_mfma_f32_16x16x32_bf16 v[4:7], v[116:119], v[152:155], v[4:7]
	v_mfma_f32_16x16x32_bf16 v[8:11], v[120:123], v[148:151], v[8:11]
	v_mfma_f32_16x16x32_bf16 v[12:15], v[120:123], v[152:155], v[12:15]
	v_mfma_f32_16x16x32_bf16 v[16:19], v[124:127], v[148:151], v[16:19]
	v_mfma_f32_16x16x32_bf16 v[20:23], v[124:127], v[152:155], v[20:23]
	v_mfma_f32_16x16x32_bf16 v[24:27], v[128:131], v[148:151], v[24:27]
; #define SK_LOAD(buf, c) do { _Pragma("unroll") for (int nt = 0; nt < 2; ++nt) fb[buf][nt] = *(const bf16x8*)(pb + nt * rs + 32 * (c)); \
;         _Pragma("unroll") for (int mt = 0; mt < NMT; ++mt) fa[buf][mt] = *(const bf16x8*)(pa + mt * rs + 32 * (c)); } while (0)
; #define SK_MMA(buf) do { _Pragma("unroll") for (int mt = 0; mt < NMT; ++mt) _Pragma("unroll") for (int nt = 0; nt < 2; ++nt) \
;         acc[mt][nt] = __builtin_amdgcn_mfma_f32_16x16x32_bf16(fa[buf][mt], fb[buf][nt], acc[mt][nt], 0, 0, 0); } while (0)
; template <int MT, class Epi>
; DI void skinny_unit(LAS unsigned char* lds, const bf16_t* A, const bf16_t* Wt, int K, int cgi, int k0, int row0, const Epi& E, int tid) {
;     ...
;     SK_LOAD(0, 0); SK_LOAD(1, 1);
;     SK_LOAD(2, 2); SK_MMA(0);
;     SK_LOAD(0, 3); SK_MMA(1);
;     SK_LOAD(1, 4); SK_MMA(2);
;     SK_LOAD(2, 5); SK_MMA(0);
;     SK_LOAD(0, 6); SK_MMA(1);
;     SK_LOAD(1, 7); SK_MMA(2);
;     SK_MMA(0); SK_MMA(1);
	v_mfma_f32_16x16x32_bf16 v[28:31], v[128:131], v[152:155], v[28:31]
	v_mfma_f32_16x16x32_bf16 v[32:35], v[132:135], v[148:151], v[32:35]
	v_mfma_f32_16x16x32_bf16 v[36:39], v[132:135], v[152:155], v[36:39]
	v_mfma_f32_16x16x32_bf16 v[40:43], v[136:139], v[148:151], v[40:43]
	v_mfma_f32_16x16x32_bf16 v[44:47], v[136:139], v[152:155], v[44:47]
	v_mfma_f32_16x16x32_bf16 v[48:51], v[140:143], v[148:151], v[48:51]
	v_mfma_f32_16x16x32_bf16 v[52:55], v[140:143], v[152:155], v[52:55]
	v_mfma_f32_16x16x32_bf16 v[56:59], v[144:147], v[148:151], v[56:59]
	v_mfma_f32_16x16x32_bf16 v[60:63], v[144:147], v[152:155], v[60:63]
	global_load_dwordx4 v[108:111], v64, s[10:11] offset:256 nt
	global_load_dwordx4 v[148:151], v64, s[10:11] offset:320 nt
	global_load_dwordx4 v[112:115], v64, s[12:13] offset:256 nt
	global_load_dwordx4 v[152:155], v64, s[12:13] offset:320 nt
	global_load_dwordx4 v[76:79], v69, s[16:17] offset:0
	global_load_dwordx4 v[80:83], v69, s[16:17] offset:1024
	global_load_dwordx4 v[84:87], v69, s[16:17] offset:2048
	global_load_dwordx4 v[88:91], v69, s[16:17] offset:3072
	s_add_u32 s16, s16, 0x1000
	s_addc_u32 s17, s17, 0
	global_load_dwordx4 v[92:95], v69, s[16:17] offset:0
	global_load_dwordx4 v[96:99], v69, s[16:17] offset:1024
	global_load_dwordx4 v[100:103], v69, s[16:17] offset:2048
	global_load_dwordx4 v[104:107], v69, s[16:17] offset:3072
	s_add_u32 s16, s16, 0x1000
	s_addc_u32 s17, s17, 0
	global_load_dwordx4 v[116:119], v69, s[16:17] offset:0
	global_load_dwordx4 v[120:123], v69, s[16:17] offset:1024
	global_load_dwordx4 v[124:127], v69, s[16:17] offset:2048
	global_load_dwordx4 v[128:131], v69, s[16:17] offset:3072
	s_add_u32 s16, s16, 0x1000
	s_addc_u32 s17, s17, 0
	global_load_dwordx4 v[132:135], v69, s[16:17] offset:0
	global_load_dwordx4 v[136:139], v69, s[16:17] offset:1024
	global_load_dwordx4 v[140:143], v69, s[16:17] offset:2048
	global_load_dwordx4 v[144:147], v69, s[16:17] offset:3072
	s_add_u32 s16, s16, 0x1000
	s_addc_u32 s17, s17, 0
	s_waitcnt vmcnt(20)
	v_mfma_f32_16x16x32_bf16 v[0:3], v[156:159], v[188:191], v[0:3]
	v_mfma_f32_16x16x32_bf16 v[4:7], v[156:159], v[192:195], v[4:7]
	v_mfma_f32_16x16x32_bf16 v[8:11], v[160:163], v[188:191], v[8:11]
	v_mfma_f32_16x16x32_bf16 v[12:15], v[160:163], v[192:195], v[12:15]
	v_mfma_f32_16x16x32_bf16 v[16:19], v[164:167], v[188:191], v[16:19]
	v_mfma_f32_16x16x32_bf16 v[20:23], v[164:167], v[192:195], v[20:23]
	v_mfma_f32_16x16x32_bf16 v[24:27], v[168:171], v[188:191], v[24:27]
	v_mfma_f32_16x16x32_bf16 v[28:31], v[168:171], v[192:195], v[28:31]
	v_mfma_f32_16x16x32_bf16 v[32:35], v[172:175], v[188:191], v[32:35]
	v_mfma_f32_16x16x32_bf16 v[36:39], v[172:175], v[192:195], v[36:39]
	v_mfma_f32_16x16x32_bf16 v[40:43], v[176:179], v[188:191], v[40:43]
	v_mfma_f32_16x16x32_bf16 v[44:47], v[176:179], v[192:195], v[44:47]
	v_mfma_f32_16x16x32_bf16 v[48:51], v[180:183], v[188:191], v[48:51]
	v_mfma_f32_16x16x32_bf16 v[52:55], v[180:183], v[192:195], v[52:55]
	v_mfma_f32_16x16x32_bf16 v[56:59], v[184:187], v[188:191], v[56:59]
	v_mfma_f32_16x16x32_bf16 v[60:63], v[184:187], v[192:195], v[60:63]
	v_mfma_f32_16x16x32_bf16 v[0:3], v[196:199], v[228:231], v[0:3]
	v_mfma_f32_16x16x32_bf16 v[4:7], v[196:199], v[232:235], v[4:7]
	v_mfma_f32_16x16x32_bf16 v[8:11], v[200:203], v[228:231], v[8:11]
	v_mfma_f32_16x16x32_bf16 v[12:15], v[200:203], v[232:235], v[12:15]
	v_mfma_f32_16x16x32_bf16 v[16:19], v[204:207], v[228:231], v[16:19]
	v_mfma_f32_16x16x32_bf16 v[20:23], v[204:207], v[232:235], v[20:23]
	v_mfma_f32_16x16x32_bf16 v[24:27], v[208:211], v[228:231], v[24:27]
	v_mfma_f32_16x16x32_bf16 v[28:31], v[208:211], v[232:235], v[28:31]
	v_mfma_f32_16x16x32_bf16 v[32:35], v[212:215], v[228:231], v[32:35]
	v_mfma_f32_16x16x32_bf16 v[36:39], v[212:215], v[232:235], v[36:39]
	v_mfma_f32_16x16x32_bf16 v[40:43], v[216:219], v[228:231], v[40:43]
	v_mfma_f32_16x16x32_bf16 v[44:47], v[216:219], v[232:235], v[44:47]
	v_mfma_f32_16x16x32_bf16 v[48:51], v[220:223], v[228:231], v[48:51]
	v_mfma_f32_16x16x32_bf16 v[52:55], v[220:223], v[232:235], v[52:55]
	v_mfma_f32_16x16x32_bf16 v[56:59], v[224:227], v[228:231], v[56:59]
	v_mfma_f32_16x16x32_bf16 v[60:63], v[224:227], v[232:235], v[60:63]
	global_load_dwordx4 v[188:191], v64, s[10:11] offset:384 nt
	global_load_dwordx4 v[228:231], v64, s[10:11] offset:448 nt
	global_load_dwordx4 v[192:195], v64, s[12:13] offset:384 nt
	global_load_dwordx4 v[232:235], v64, s[12:13] offset:448 nt
	global_load_dwordx4 v[156:159], v69, s[16:17] offset:0
	global_load_dwordx4 v[160:163], v69, s[16:17] offset:1024
	global_load_dwordx4 v[164:167], v69, s[16:17] offset:2048
	global_load_dwordx4 v[168:171], v69, s[16:17] offset:3072
	s_add_u32 s16, s16, 0x1000
	s_addc_u32 s17, s17, 0
	global_load_dwordx4 v[172:175], v69, s[16:17] offset:0
	global_load_dwordx4 v[176:179], v69, s[16:17] offset:1024
	global_load_dwordx4 v[180:183], v69, s[16:17] offset:2048
	global_load_dwordx4 v[184:187], v69, s[16:17] offset:3072
	s_add_u32 s16, s16, 0x1000
	s_addc_u32 s17, s17, 0
	global_load_dwordx4 v[196:199], v69, s[16:17] offset:0
	global_load_dwordx4 v[200:203], v69, s[16:17] offset:1024
	global_load_dwordx4 v[204:207], v69, s[16:17] offset:2048
	global_load_dwordx4 v[208:211], v69, s[16:17] offset:3072
	s_add_u32 s16, s16, 0x1000
	s_addc_u32 s17, s17, 0
	global_load_dwordx4 v[212:215], v69, s[16:17] offset:0
	global_load_dwordx4 v[216:219], v69, s[16:17] offset:1024
	global_load_dwordx4 v[220:223], v69, s[16:17] offset:2048
	global_load_dwordx4 v[224:227], v69, s[16:17] offset:3072
	s_waitcnt vmcnt(20)
; #define LAS __attribute__((address_space(3)))
; #define SK_LOAD(buf, c) do { _Pragma("unroll") for (int nt = 0; nt < 2; ++nt) fb[buf][nt] = *(const bf16x8*)(pb + nt * rs + 32 * (c)); \
;         _Pragma("unroll") for (int mt = 0; mt < NMT; ++mt) fa[buf][mt] = *(const bf16x8*)(pa + mt * rs + 32 * (c)); } while (0)
; #define SK_MMA(buf) do { _Pragma("unroll") for (int mt = 0; mt < NMT; ++mt) _Pragma("unroll") for (int nt = 0; nt < 2; ++nt) \
;         acc[mt][nt] = __builtin_amdgcn_mfma_f32_16x16x32_bf16(fa[buf][mt], fb[buf][nt], acc[mt][nt], 0, 0, 0); } while (0)
; template <int MT, class Epi>
; DI void skinny_unit(LAS unsigned char* lds, const bf16_t* A, const bf16_t* Wt, int K, int cgi, int k0, int row0, const Epi& E, int tid) {
;     ...
;     SK_LOAD(0, 0); SK_LOAD(1, 1);
;     SK_LOAD(2, 2); SK_MMA(0);
;     SK_LOAD(0, 3); SK_MMA(1);
;     SK_LOAD(1, 4); SK_MMA(2);
;     SK_LOAD(2, 5); SK_MMA(0);
;     SK_LOAD(0, 6); SK_MMA(1);
;     SK_LOAD(1, 7); SK_MMA(2);
;     SK_MMA(0); SK_MMA(1);
;     ...
;     constexpr int NR = 32 * MT;
;     LAS float* red = (LAS float*)lds;
; #pragma unroll
;     for (int mt = 0; mt < NMT; ++mt)
; #pragma unroll
;         for (int nt = 0; nt < 2; ++nt)
; #pragma unroll
;             for (int j = 0; j < 4; ++j) red[(wid * NR + mt * 16 + 4 * fq + j) * 32 + nt * 16 + fr] = acc[mt][nt][j];
	v_mfma_f32_16x16x32_bf16 v[0:3], v[76:79], v[108:111], v[0:3]
	v_mfma_f32_16x16x32_bf16 v[4:7], v[76:79], v[112:115], v[4:7]
	v_mfma_f32_16x16x32_bf16 v[8:11], v[80:83], v[108:111], v[8:11]
	v_mfma_f32_16x16x32_bf16 v[12:15], v[80:83], v[112:115], v[12:15]
	v_mfma_f32_16x16x32_bf16 v[16:19], v[84:87], v[108:111], v[16:19]
	v_mfma_f32_16x16x32_bf16 v[20:23], v[84:87], v[112:115], v[20:23]
	v_mfma_f32_16x16x32_bf16 v[24:27], v[88:91], v[108:111], v[24:27]
	v_mfma_f32_16x16x32_bf16 v[28:31], v[88:91], v[112:115], v[28:31]
	v_mfma_f32_16x16x32_bf16 v[32:35], v[92:95], v[108:111], v[32:35]
	v_mfma_f32_16x16x32_bf16 v[36:39], v[92:95], v[112:115], v[36:39]
	v_mfma_f32_16x16x32_bf16 v[40:43], v[96:99], v[108:111], v[40:43]
	v_mfma_f32_16x16x32_bf16 v[44:47], v[96:99], v[112:115], v[44:47]
	v_mfma_f32_16x16x32_bf16 v[48:51], v[100:103], v[108:111], v[48:51]
	v_mfma_f32_16x16x32_bf16 v[52:55], v[100:103], v[112:115], v[52:55]
	v_mfma_f32_16x16x32_bf16 v[56:59], v[104:107], v[108:111], v[56:59]
	v_mfma_f32_16x16x32_bf16 v[60:63], v[104:107], v[112:115], v[60:63]
	v_mfma_f32_16x16x32_bf16 v[0:3], v[116:119], v[148:151], v[0:3]
	v_mfma_f32_16x16x32_bf16 v[4:7], v[116:119], v[152:155], v[4:7]
	v_mfma_f32_16x16x32_bf16 v[8:11], v[120:123], v[148:151], v[8:11]
	v_mfma_f32_16x16x32_bf16 v[12:15], v[120:123], v[152:155], v[12:15]
	v_mfma_f32_16x16x32_bf16 v[16:19], v[124:127], v[148:151], v[16:19]
	v_mfma_f32_16x16x32_bf16 v[20:23], v[124:127], v[152:155], v[20:23]
	v_mfma_f32_16x16x32_bf16 v[24:27], v[128:131], v[148:151], v[24:27]
	v_mfma_f32_16x16x32_bf16 v[28:31], v[128:131], v[152:155], v[28:31]
	v_mfma_f32_16x16x32_bf16 v[32:35], v[132:135], v[148:151], v[32:35]
	v_mfma_f32_16x16x32_bf16 v[36:39], v[132:135], v[152:155], v[36:39]
	v_mfma_f32_16x16x32_bf16 v[40:43], v[136:139], v[148:151], v[40:43]
	v_mfma_f32_16x16x32_bf16 v[44:47], v[136:139], v[152:155], v[44:47]
	v_mfma_f32_16x16x32_bf16 v[48:51], v[140:143], v[148:151], v[48:51]
	v_mfma_f32_16x16x32_bf16 v[52:55], v[140:143], v[152:155], v[52:55]
	v_mfma_f32_16x16x32_bf16 v[56:59], v[144:147], v[148:151], v[56:59]
	v_mfma_f32_16x16x32_bf16 v[60:63], v[144:147], v[152:155], v[60:63]
	s_waitcnt vmcnt(0)
	v_mfma_f32_16x16x32_bf16 v[0:3], v[156:159], v[188:191], v[0:3]
	v_mfma_f32_16x16x32_bf16 v[4:7], v[156:159], v[192:195], v[4:7]
	v_mfma_f32_16x16x32_bf16 v[8:11], v[160:163], v[188:191], v[8:11]
	v_mfma_f32_16x16x32_bf16 v[12:15], v[160:163], v[192:195], v[12:15]
	v_mfma_f32_16x16x32_bf16 v[16:19], v[164:167], v[188:191], v[16:19]
	v_mfma_f32_16x16x32_bf16 v[20:23], v[164:167], v[192:195], v[20:23]
	v_mfma_f32_16x16x32_bf16 v[24:27], v[168:171], v[188:191], v[24:27]
	v_mfma_f32_16x16x32_bf16 v[28:31], v[168:171], v[192:195], v[28:31]
	v_mfma_f32_16x16x32_bf16 v[32:35], v[172:175], v[188:191], v[32:35]
	v_mfma_f32_16x16x32_bf16 v[36:39], v[172:175], v[192:195], v[36:39]
	v_mfma_f32_16x16x32_bf16 v[40:43], v[176:179], v[188:191], v[40:43]
	v_mfma_f32_16x16x32_bf16 v[44:47], v[176:179], v[192:195], v[44:47]
	v_mfma_f32_16x16x32_bf16 v[48:51], v[180:183], v[188:191], v[48:51]
	v_mfma_f32_16x16x32_bf16 v[52:55], v[180:183], v[192:195], v[52:55]
	v_mfma_f32_16x16x32_bf16 v[56:59], v[184:187], v[188:191], v[56:59]
	v_mfma_f32_16x16x32_bf16 v[60:63], v[184:187], v[192:195], v[60:63]
	v_mfma_f32_16x16x32_bf16 v[0:3], v[196:199], v[228:231], v[0:3]
	v_mfma_f32_16x16x32_bf16 v[4:7], v[196:199], v[232:235], v[4:7]
	v_mfma_f32_16x16x32_bf16 v[8:11], v[200:203], v[228:231], v[8:11]
	v_mfma_f32_16x16x32_bf16 v[12:15], v[200:203], v[232:235], v[12:15]
	v_mfma_f32_16x16x32_bf16 v[16:19], v[204:207], v[228:231], v[16:19]
	v_mfma_f32_16x16x32_bf16 v[20:23], v[204:207], v[232:235], v[20:23]
	v_mfma_f32_16x16x32_bf16 v[24:27], v[208:211], v[228:231], v[24:27]
	v_mfma_f32_16x16x32_bf16 v[28:31], v[208:211], v[232:235], v[28:31]
	v_mfma_f32_16x16x32_bf16 v[32:35], v[212:215], v[228:231], v[32:35]
	v_mfma_f32_16x16x32_bf16 v[36:39], v[212:215], v[232:235], v[36:39]
	v_mfma_f32_16x16x32_bf16 v[40:43], v[216:219], v[228:231], v[40:43]
	v_mfma_f32_16x16x32_bf16 v[44:47], v[216:219], v[232:235], v[44:47]
	v_mfma_f32_16x16x32_bf16 v[48:51], v[220:223], v[228:231], v[48:51]
	v_mfma_f32_16x16x32_bf16 v[52:55], v[220:223], v[232:235], v[52:55]
	v_mfma_f32_16x16x32_bf16 v[56:59], v[224:227], v[228:231], v[56:59]
	v_mfma_f32_16x16x32_bf16 v[60:63], v[224:227], v[232:235], v[60:63]
	v_add_u32_e32 v77, 0x800, v65
	v_add_u32_e32 v78, 0x1000, v65
	v_add_u32_e32 v79, 0x1800, v65
	v_add_u32_e32 v80, 0x2000, v65
	v_add_u32_e32 v81, 0x2800, v65
	v_add_u32_e32 v82, 0x3000, v65
	v_add_u32_e32 v83, 0x3800, v65
	s_nop 7
	s_nop 3
	ds_write2_b32 v65, v0, v4 offset1:16
	ds_write2_b32 v65, v1, v5 offset0:32 offset1:48
	ds_write2_b32 v65, v2, v6 offset0:64 offset1:80
	ds_write2_b32 v65, v3, v7 offset0:96 offset1:112
	ds_write2_b32 v77, v8, v12 offset1:16
	ds_write2_b32 v77, v9, v13 offset0:32 offset1:48
	ds_write2_b32 v77, v10, v14 offset0:64 offset1:80
	ds_write2_b32 v77, v11, v15 offset0:96 offset1:112
	ds_write2_b32 v78, v16, v20 offset1:16
	ds_write2_b32 v78, v17, v21 offset0:32 offset1:48
	ds_write2_b32 v78, v18, v22 offset0:64 offset1:80
	ds_write2_b32 v78, v19, v23 offset0:96 offset1:112
	ds_write2_b32 v79, v24, v28 offset1:16
	ds_write2_b32 v79, v25, v29 offset0:32 offset1:48
	ds_write2_b32 v79, v26, v30 offset0:64 offset1:80
	ds_write2_b32 v79, v27, v31 offset0:96 offset1:112
	ds_write2_b32 v80, v32, v36 offset1:16
	ds_write2_b32 v80, v33, v37 offset0:32 offset1:48
	ds_write2_b32 v80, v34, v38 offset0:64 offset1:80
	ds_write2_b32 v80, v35, v39 offset0:96 offset1:112
	ds_write2_b32 v81, v40, v44 offset1:16
	ds_write2_b32 v81, v41, v45 offset0:32 offset1:48
	ds_write2_b32 v81, v42, v46 offset0:64 offset1:80
	ds_write2_b32 v81, v43, v47 offset0:96 offset1:112
	ds_write2_b32 v82, v48, v52 offset1:16
	ds_write2_b32 v82, v49, v53 offset0:32 offset1:48
	ds_write2_b32 v82, v50, v54 offset0:64 offset1:80
	ds_write2_b32 v82, v51, v55 offset0:96 offset1:112
	ds_write2_b32 v83, v56, v60 offset1:16
	ds_write2_b32 v83, v57, v61 offset0:32 offset1:48
	ds_write2_b32 v83, v58, v62 offset0:64 offset1:80
	ds_write2_b32 v83, v59, v63 offset0:96 offset1:112
	s_waitcnt lgkmcnt(0)
	s_barrier
; #define LAS __attribute__((address_space(3)))
; template <int MT, class Epi>
; DI void skinny_unit(LAS unsigned char* lds, const bf16_t* A, const bf16_t* Wt, int K, int cgi, int k0, int row0, const Epi& E, int tid) {
;     ...
;     __syncthreads();
;     if (MT == 4) {
;         const int row = tid >> 2, c8 = (tid & 3) * 8;
;         f32x4 sa = {0.f, 0.f, 0.f, 0.f}, sb = {0.f, 0.f, 0.f, 0.f};
; #pragma unroll
;         for (int w = 0; w < 8; ++w) { sa += *(const LAS f32x4*)(red + (w * NR + row) * 32 + c8); sb += *(const LAS f32x4*)(red + (w * NR + row) * 32 + c8 + 4); }
;         E(row0 + row, c0 + c8, sa); E(row0 + row, c0 + c8 + 4, sb);
;     } else if (tid < 8 * NR) {
;         const int row = tid >> 3, c4 = (tid & 7) * 4;
;         f32x4 sa = {0.f, 0.f, 0.f, 0.f};
; #pragma unroll
;         for (int w = 0; w < 8; ++w) sa += *(const LAS f32x4*)(red + (w * NR + row) * 32 + c4);
;         E(row0 + row, c0 + c4, sa);
;     }
;     __syncthreads();
; }
	ds_read_b128 v[76:79], v66 offset:0
	ds_read_b128 v[80:83], v66 offset:16
	ds_read_b128 v[84:87], v66 offset:16384
	ds_read_b128 v[88:91], v66 offset:16400
	ds_read_b128 v[92:95], v66 offset:32768
	ds_read_b128 v[96:99], v66 offset:32784
	ds_read_b128 v[100:103], v66 offset:49152
	ds_read_b128 v[104:107], v66 offset:49168
	ds_read_b128 v[108:111], v67 offset:0
	ds_read_b128 v[112:115], v67 offset:16
	ds_read_b128 v[116:119], v67 offset:16384
	ds_read_b128 v[120:123], v67 offset:16400
	ds_read_b128 v[124:127], v67 offset:32768
	ds_read_b128 v[128:131], v67 offset:32784
	ds_read_b128 v[132:135], v67 offset:49152
	ds_read_b128 v[136:139], v67 offset:49168
	s_waitcnt lgkmcnt(12)
	v_pk_add_f32 v[76:77], v[76:77], v[84:85]
	v_pk_add_f32 v[78:79], v[78:79], v[86:87]
	v_pk_add_f32 v[80:81], v[80:81], v[88:89]
	v_pk_add_f32 v[82:83], v[82:83], v[90:91]
	s_waitcnt lgkmcnt(10)
	v_pk_add_f32 v[76:77], v[76:77], v[92:93]
	v_pk_add_f32 v[78:79], v[78:79], v[94:95]
	v_pk_add_f32 v[80:81], v[80:81], v[96:97]
	v_pk_add_f32 v[82:83], v[82:83], v[98:99]
	s_waitcnt lgkmcnt(8)
	v_pk_add_f32 v[76:77], v[76:77], v[100:101]
	v_pk_add_f32 v[78:79], v[78:79], v[102:103]
	v_pk_add_f32 v[80:81], v[80:81], v[104:105]
	v_pk_add_f32 v[82:83], v[82:83], v[106:107]
	s_waitcnt lgkmcnt(6)
	v_pk_add_f32 v[76:77], v[76:77], v[108:109]
	v_pk_add_f32 v[78:79], v[78:79], v[110:111]
	v_pk_add_f32 v[80:81], v[80:81], v[112:113]
	v_pk_add_f32 v[82:83], v[82:83], v[114:115]
	s_waitcnt lgkmcnt(4)
	v_pk_add_f32 v[76:77], v[76:77], v[116:117]
	v_pk_add_f32 v[78:79], v[78:79], v[118:119]
	v_pk_add_f32 v[80:81], v[80:81], v[120:121]
	v_pk_add_f32 v[82:83], v[82:83], v[122:123]
	s_waitcnt lgkmcnt(2)
	v_pk_add_f32 v[76:77], v[76:77], v[124:125]
	v_pk_add_f32 v[78:79], v[78:79], v[126:127]
	v_pk_add_f32 v[80:81], v[80:81], v[128:129]
	v_pk_add_f32 v[82:83], v[82:83], v[130:131]
	s_waitcnt lgkmcnt(0)
	v_pk_add_f32 v[76:77], v[76:77], v[132:133]
	v_pk_add_f32 v[78:79], v[78:79], v[134:135]
	v_pk_add_f32 v[80:81], v[80:81], v[136:137]
	v_pk_add_f32 v[82:83], v[82:83], v[138:139]
	global_store_dwordx4 v68, v[76:79], s[14:15]
	global_store_dwordx4 v68, v[80:83], s[14:15] offset:16
	s_add_i32 s0, s0, s64
	s_cmpk_lt_i32 s0, 0x100
	s_barrier
	s_cbranch_scc1 .Lsk7b_loop
